# K-loop load segments: LDS-DMA issue blocks placed before the segment's LDS reads (no setprio)
# baseline (speedup 1.0000x reference)
.Lnb_p1:
	s_add_i32 s7, s4, 0xfff84000
	s_cmp_eq_u32 s6, 28
	s_cselect_b32 s17, s0, s7
	s_cselect_b32 s16, s1, s5
	s_or_b32 s7, s17, 0x4000
	s_mov_b32 m0, s79
	s_nop 0
	buffer_load_dwordx4 v242, s[24:27], s4 offen lds
	s_nop 0
	s_mov_b32 m0, s83
	s_nop 0
	buffer_load_dwordx4 v243, s[24:27], s4 offen lds
	s_waitcnt vmcnt(24)
	s_waitcnt lgkmcnt(0)
	s_barrier
	s_waitcnt lgkmcnt(7)
	v_mfma_f32_16x16x32_bf16 v[180:183], v[16:19], v[192:195], 0
	v_mfma_f32_16x16x32_bf16 v[164:167], v[24:27], v[192:195], 0
	s_waitcnt lgkmcnt(5)
	v_mfma_f32_16x16x32_bf16 v[148:151], v[16:19], v[200:203], 0
	v_mfma_f32_16x16x32_bf16 v[140:143], v[24:27], v[200:203], 0
	s_waitcnt lgkmcnt(3)
	v_mfma_f32_16x16x32_bf16 v[132:135], v[16:19], v[220:223], 0
	v_mfma_f32_16x16x32_bf16 v[124:127], v[24:27], v[220:223], 0
	s_waitcnt lgkmcnt(1)
	v_mfma_f32_16x16x32_bf16 v[116:119], v[16:19], v[228:231], 0
	v_mfma_f32_16x16x32_bf16 v[108:111], v[24:27], v[228:231], 0
	v_mfma_f32_16x16x32_bf16 v[180:183], v[20:23], v[196:199], v[180:183]
	v_mfma_f32_16x16x32_bf16 v[164:167], v[28:31], v[196:199], v[164:167]
	v_mfma_f32_16x16x32_bf16 v[148:151], v[20:23], v[204:207], v[148:151]
	v_mfma_f32_16x16x32_bf16 v[140:143], v[28:31], v[204:207], v[140:143]
	v_mfma_f32_16x16x32_bf16 v[132:135], v[20:23], v[224:227], v[132:135]
	v_mfma_f32_16x16x32_bf16 v[124:127], v[28:31], v[224:227], v[124:127]
	s_waitcnt lgkmcnt(0)
	v_mfma_f32_16x16x32_bf16 v[116:119], v[20:23], v[246:249], v[116:119]
	v_mfma_f32_16x16x32_bf16 v[108:111], v[28:31], v[246:249], v[108:111]
	v_mfma_f32_16x16x32_bf16 v[172:175], v[152:155], v[192:195], 0
	v_mfma_f32_16x16x32_bf16 v[156:159], v[168:171], v[192:195], 0
	v_mfma_f32_16x16x32_bf16 v[144:147], v[152:155], v[200:203], 0
	v_mfma_f32_16x16x32_bf16 v[136:139], v[168:171], v[200:203], 0
	v_mfma_f32_16x16x32_bf16 v[128:131], v[152:155], v[220:223], 0
	v_mfma_f32_16x16x32_bf16 v[120:123], v[168:171], v[220:223], 0
	v_mfma_f32_16x16x32_bf16 v[112:115], v[152:155], v[228:231], 0
	v_mfma_f32_16x16x32_bf16 v[104:107], v[168:171], v[228:231], 0
	v_mfma_f32_16x16x32_bf16 v[172:175], v[160:163], v[196:199], v[172:175]
	v_mfma_f32_16x16x32_bf16 v[156:159], v[176:179], v[196:199], v[156:159]
	v_mfma_f32_16x16x32_bf16 v[144:147], v[160:163], v[204:207], v[144:147]
	v_mfma_f32_16x16x32_bf16 v[136:139], v[176:179], v[204:207], v[136:139]
	v_mfma_f32_16x16x32_bf16 v[128:131], v[160:163], v[224:227], v[128:131]
	v_mfma_f32_16x16x32_bf16 v[120:123], v[176:179], v[224:227], v[120:123]
	v_mfma_f32_16x16x32_bf16 v[112:115], v[160:163], v[246:249], v[112:115]
	v_mfma_f32_16x16x32_bf16 v[104:107], v[176:179], v[246:249], v[104:107]
	s_barrier
	s_mov_b32 m0, s51
	s_nop 0
	buffer_load_dwordx4 v242, s[56:59], s16 offen lds
	s_add_i32 s18, s16, 0x80000
	s_mov_b32 m0, s52
	s_nop 0
	buffer_load_dwordx4 v243, s[56:59], s16 offen lds
	s_nop 0
	s_mov_b32 m0, s53
	s_nop 0
	buffer_load_dwordx4 v242, s[56:59], s18 offen lds
	s_nop 0
	s_mov_b32 m0, s55
	s_nop 0
	buffer_load_dwordx4 v243, s[56:59], s18 offen lds
	s_nop 0
	s_mov_b32 m0, s31
	s_nop 0
	buffer_load_dwordx4 v242, s[24:27], s17 offen lds
	s_nop 0
	s_mov_b32 m0, s68
	s_nop 0
	buffer_load_dwordx4 v243, s[24:27], s17 offen lds
	ds_read_b128 v[192:195], v245 offset:16384
	ds_read_b128 v[196:199], v245 offset:17408
	ds_read_b128 v[200:203], v245 offset:18432
	ds_read_b128 v[204:207], v245 offset:19456
	ds_read_b128 v[220:223], v245 offset:20480
	ds_read_b128 v[224:227], v245 offset:21504
	ds_read_b128 v[228:231], v245 offset:22528
	ds_read_b128 v[246:249], v245 offset:23552
	s_waitcnt vmcnt(24)
	s_waitcnt lgkmcnt(0)
	s_barrier
	s_waitcnt lgkmcnt(7)
	v_mfma_f32_16x16x32_bf16 v[76:79], v[16:19], v[192:195], 0
	v_mfma_f32_16x16x32_bf16 v[68:71], v[24:27], v[192:195], 0
	s_waitcnt lgkmcnt(5)
	v_mfma_f32_16x16x32_bf16 v[60:63], v[16:19], v[200:203], 0
	v_mfma_f32_16x16x32_bf16 v[52:55], v[24:27], v[200:203], 0
	s_waitcnt lgkmcnt(3)
	v_mfma_f32_16x16x32_bf16 v[44:47], v[16:19], v[220:223], 0
	v_mfma_f32_16x16x32_bf16 v[36:39], v[24:27], v[220:223], 0
	s_waitcnt lgkmcnt(1)
	v_mfma_f32_16x16x32_bf16 v[12:15], v[16:19], v[228:231], 0
	v_mfma_f32_16x16x32_bf16 v[4:7], v[24:27], v[228:231], 0
	v_mfma_f32_16x16x32_bf16 v[76:79], v[20:23], v[196:199], v[76:79]
	v_mfma_f32_16x16x32_bf16 v[68:71], v[28:31], v[196:199], v[68:71]
	v_mfma_f32_16x16x32_bf16 v[60:63], v[20:23], v[204:207], v[60:63]
	v_mfma_f32_16x16x32_bf16 v[52:55], v[28:31], v[204:207], v[52:55]
	v_mfma_f32_16x16x32_bf16 v[44:47], v[20:23], v[224:227], v[44:47]
	v_mfma_f32_16x16x32_bf16 v[36:39], v[28:31], v[224:227], v[36:39]
	s_waitcnt lgkmcnt(0)
	v_mfma_f32_16x16x32_bf16 v[12:15], v[20:23], v[246:249], v[12:15]
	v_mfma_f32_16x16x32_bf16 v[4:7], v[28:31], v[246:249], v[4:7]
	v_mfma_f32_16x16x32_bf16 v[40:43], v[152:155], v[220:223], 0
	v_mfma_f32_16x16x32_bf16 v[32:35], v[168:171], v[220:223], 0
	v_mfma_f32_16x16x32_bf16 v[8:11], v[152:155], v[228:231], 0
	v_mfma_f32_16x16x32_bf16 v[0:3], v[168:171], v[228:231], 0
	v_mfma_f32_16x16x32_bf16 v[16:19], v[152:155], v[192:195], 0
	v_mfma_f32_16x16x32_bf16 v[20:23], v[168:171], v[192:195], 0
	v_mfma_f32_16x16x32_bf16 v[24:27], v[152:155], v[200:203], 0
	v_mfma_f32_16x16x32_bf16 v[28:31], v[168:171], v[200:203], 0
	v_mfma_f32_16x16x32_bf16 v[40:43], v[160:163], v[224:227], v[40:43]
	v_mfma_f32_16x16x32_bf16 v[32:35], v[176:179], v[224:227], v[32:35]
	v_mfma_f32_16x16x32_bf16 v[8:11], v[160:163], v[246:249], v[8:11]
	v_mfma_f32_16x16x32_bf16 v[0:3], v[176:179], v[246:249], v[0:3]
	v_mfma_f32_16x16x32_bf16 v[16:19], v[160:163], v[196:199], v[16:19]
	v_mfma_f32_16x16x32_bf16 v[20:23], v[176:179], v[196:199], v[20:23]
	v_mfma_f32_16x16x32_bf16 v[24:27], v[160:163], v[204:207], v[24:27]
	v_mfma_f32_16x16x32_bf16 v[28:31], v[176:179], v[204:207], v[28:31]
	s_barrier
	s_add_i32 s17, s17, 0x80000
	s_mov_b32 m0, s69
	s_nop 0
	buffer_load_dwordx4 v242, s[24:27], s17 offen lds
	s_nop 0
	s_mov_b32 m0, s70
	s_nop 0
	buffer_load_dwordx4 v243, s[24:27], s17 offen lds
	v_add_u32_e32 v72, 0x18000, v83
	v_add_u32_e32 v80, 0x1c000, v83
	ds_read_b128 v[48:51], v72
	ds_read_b128 v[56:59], v72 offset:1024
	ds_read_b128 v[64:67], v72 offset:2048
	ds_read_b128 v[72:75], v72 offset:3072
	ds_read_b128 v[152:155], v80
	ds_read_b128 v[160:163], v80 offset:1024
	ds_read_b128 v[168:171], v80 offset:2048
	ds_read_b128 v[176:179], v80 offset:3072
	ds_read_b128 v[192:195], v245 offset:32768
	ds_read_b128 v[196:199], v245 offset:33792
	ds_read_b128 v[200:203], v245 offset:34816
	ds_read_b128 v[204:207], v245 offset:35840
	ds_read_b128 v[220:223], v245 offset:36864
	ds_read_b128 v[224:227], v245 offset:37888
	ds_read_b128 v[228:231], v245 offset:38912
	ds_read_b128 v[246:249], v245 offset:39936
	s_waitcnt vmcnt(8)
	s_waitcnt lgkmcnt(0)
	s_barrier
	s_waitcnt lgkmcnt(7)
	v_mfma_f32_16x16x32_bf16 v[180:183], v[48:51], v[192:195], v[180:183]
	v_mfma_f32_16x16x32_bf16 v[164:167], v[64:67], v[192:195], v[164:167]
	s_waitcnt lgkmcnt(5)
	v_mfma_f32_16x16x32_bf16 v[148:151], v[48:51], v[200:203], v[148:151]
	v_mfma_f32_16x16x32_bf16 v[140:143], v[64:67], v[200:203], v[140:143]
	s_waitcnt lgkmcnt(3)
	v_mfma_f32_16x16x32_bf16 v[132:135], v[48:51], v[220:223], v[132:135]
	v_mfma_f32_16x16x32_bf16 v[124:127], v[64:67], v[220:223], v[124:127]
	s_waitcnt lgkmcnt(1)
	v_mfma_f32_16x16x32_bf16 v[116:119], v[48:51], v[228:231], v[116:119]
	v_mfma_f32_16x16x32_bf16 v[108:111], v[64:67], v[228:231], v[108:111]
	v_mfma_f32_16x16x32_bf16 v[180:183], v[56:59], v[196:199], v[180:183]
	v_mfma_f32_16x16x32_bf16 v[164:167], v[72:75], v[196:199], v[164:167]
	v_mfma_f32_16x16x32_bf16 v[148:151], v[56:59], v[204:207], v[148:151]
	v_mfma_f32_16x16x32_bf16 v[140:143], v[72:75], v[204:207], v[140:143]
	v_mfma_f32_16x16x32_bf16 v[132:135], v[56:59], v[224:227], v[132:135]
	v_mfma_f32_16x16x32_bf16 v[124:127], v[72:75], v[224:227], v[124:127]
	s_waitcnt lgkmcnt(0)
	v_mfma_f32_16x16x32_bf16 v[116:119], v[56:59], v[246:249], v[116:119]
	v_mfma_f32_16x16x32_bf16 v[108:111], v[72:75], v[246:249], v[108:111]
	v_mfma_f32_16x16x32_bf16 v[172:175], v[152:155], v[192:195], v[172:175]
	v_mfma_f32_16x16x32_bf16 v[156:159], v[168:171], v[192:195], v[156:159]
	v_mfma_f32_16x16x32_bf16 v[144:147], v[152:155], v[200:203], v[144:147]
	v_mfma_f32_16x16x32_bf16 v[136:139], v[168:171], v[200:203], v[136:139]
	v_mfma_f32_16x16x32_bf16 v[128:131], v[152:155], v[220:223], v[128:131]
	v_mfma_f32_16x16x32_bf16 v[120:123], v[168:171], v[220:223], v[120:123]
	v_mfma_f32_16x16x32_bf16 v[112:115], v[152:155], v[228:231], v[112:115]
	v_mfma_f32_16x16x32_bf16 v[104:107], v[168:171], v[228:231], v[104:107]
	v_mfma_f32_16x16x32_bf16 v[172:175], v[160:163], v[196:199], v[172:175]
	v_mfma_f32_16x16x32_bf16 v[156:159], v[176:179], v[196:199], v[156:159]
	v_mfma_f32_16x16x32_bf16 v[144:147], v[160:163], v[204:207], v[144:147]
	v_mfma_f32_16x16x32_bf16 v[136:139], v[176:179], v[204:207], v[136:139]
	v_mfma_f32_16x16x32_bf16 v[128:131], v[160:163], v[224:227], v[128:131]
	v_mfma_f32_16x16x32_bf16 v[120:123], v[176:179], v[224:227], v[120:123]
	v_mfma_f32_16x16x32_bf16 v[112:115], v[160:163], v[246:249], v[112:115]
	v_mfma_f32_16x16x32_bf16 v[104:107], v[176:179], v[246:249], v[104:107]
	s_barrier
	s_or_b32 s17, s16, 0x4000
	s_mov_b32 m0, s73
	s_nop 0
	buffer_load_dwordx4 v242, s[56:59], s17 offen lds
	s_add_i32 s16, s16, 0x84000
	s_mov_b32 m0, s74
	s_nop 0
	buffer_load_dwordx4 v243, s[56:59], s17 offen lds
	s_nop 0
	s_mov_b32 m0, s77
	s_nop 0
	buffer_load_dwordx4 v242, s[56:59], s16 offen lds
	s_nop 0
	s_mov_b32 m0, s78
	s_nop 0
	buffer_load_dwordx4 v243, s[56:59], s16 offen lds
	s_nop 0
	s_mov_b32 m0, s75
	s_nop 0
	buffer_load_dwordx4 v242, s[24:27], s7 offen lds
	s_nop 0
	s_mov_b32 m0, s76
	s_nop 0
	buffer_load_dwordx4 v243, s[24:27], s7 offen lds
	ds_read_b128 v[192:195], v245 offset:49152
	ds_read_b128 v[196:199], v245 offset:50176
	ds_read_b128 v[200:203], v245 offset:51200
	ds_read_b128 v[204:207], v245 offset:52224
	ds_read_b128 v[220:223], v245 offset:53248
	ds_read_b128 v[224:227], v245 offset:54272
	ds_read_b128 v[228:231], v245 offset:55296
	ds_read_b128 v[246:249], v245 offset:56320
	s_waitcnt vmcnt(8)
	s_waitcnt lgkmcnt(0)
	s_barrier
	s_waitcnt lgkmcnt(7)
	v_mfma_f32_16x16x32_bf16 v[76:79], v[48:51], v[192:195], v[76:79]
	v_mfma_f32_16x16x32_bf16 v[68:71], v[64:67], v[192:195], v[68:71]
	s_waitcnt lgkmcnt(5)
	v_mfma_f32_16x16x32_bf16 v[60:63], v[48:51], v[200:203], v[60:63]
	v_mfma_f32_16x16x32_bf16 v[52:55], v[64:67], v[200:203], v[52:55]
	s_waitcnt lgkmcnt(3)
	v_mfma_f32_16x16x32_bf16 v[44:47], v[48:51], v[220:223], v[44:47]
	v_mfma_f32_16x16x32_bf16 v[36:39], v[64:67], v[220:223], v[36:39]
	s_waitcnt lgkmcnt(1)
	v_mfma_f32_16x16x32_bf16 v[12:15], v[48:51], v[228:231], v[12:15]
	v_mfma_f32_16x16x32_bf16 v[4:7], v[64:67], v[228:231], v[4:7]
	v_mfma_f32_16x16x32_bf16 v[76:79], v[56:59], v[196:199], v[76:79]
	v_mfma_f32_16x16x32_bf16 v[68:71], v[72:75], v[196:199], v[68:71]
	v_mfma_f32_16x16x32_bf16 v[60:63], v[56:59], v[204:207], v[60:63]
	v_mfma_f32_16x16x32_bf16 v[52:55], v[72:75], v[204:207], v[52:55]
	v_mfma_f32_16x16x32_bf16 v[44:47], v[56:59], v[224:227], v[44:47]
	v_mfma_f32_16x16x32_bf16 v[36:39], v[72:75], v[224:227], v[36:39]
	s_waitcnt lgkmcnt(0)
	v_mfma_f32_16x16x32_bf16 v[12:15], v[56:59], v[246:249], v[12:15]
	v_mfma_f32_16x16x32_bf16 v[4:7], v[72:75], v[246:249], v[4:7]
	v_mfma_f32_16x16x32_bf16 v[16:19], v[152:155], v[192:195], v[16:19]
	v_mfma_f32_16x16x32_bf16 v[72:75], v[160:163], v[196:199], v[16:19]
	v_mfma_f32_16x16x32_bf16 v[16:19], v[168:171], v[192:195], v[20:23]
	v_mfma_f32_16x16x32_bf16 v[64:67], v[176:179], v[196:199], v[16:19]
	v_mfma_f32_16x16x32_bf16 v[16:19], v[152:155], v[200:203], v[24:27]
	v_mfma_f32_16x16x32_bf16 v[56:59], v[160:163], v[204:207], v[16:19]
	v_mfma_f32_16x16x32_bf16 v[16:19], v[168:171], v[200:203], v[28:31]
	v_mfma_f32_16x16x32_bf16 v[48:51], v[176:179], v[204:207], v[16:19]
	v_mfma_f32_16x16x32_bf16 v[16:19], v[152:155], v[220:223], v[40:43]
	v_mfma_f32_16x16x32_bf16 v[40:43], v[160:163], v[224:227], v[16:19]
	v_mfma_f32_16x16x32_bf16 v[16:19], v[168:171], v[220:223], v[32:35]
	v_mfma_f32_16x16x32_bf16 v[8:11], v[152:155], v[228:231], v[8:11]
	v_mfma_f32_16x16x32_bf16 v[0:3], v[168:171], v[228:231], v[0:3]
	v_mfma_f32_16x16x32_bf16 v[32:35], v[176:179], v[224:227], v[16:19]
	v_mfma_f32_16x16x32_bf16 v[8:11], v[160:163], v[246:249], v[8:11]
	v_mfma_f32_16x16x32_bf16 v[0:3], v[176:179], v[246:249], v[0:3]
	s_barrier
	s_add_i32 s6, s6, 2
	s_add_i32 s4, s4, 0x8000
	s_add_i32 s5, s5, 0x8000
.LBB0_143:
	v_add_u32_e32 v28, 0x10000, v83
	v_add_u32_e32 v80, 0x14000, v83
	ds_read_b128 v[16:19], v28
	ds_read_b128 v[20:23], v28 offset:1024
	ds_read_b128 v[24:27], v28 offset:2048
	ds_read_b128 v[28:31], v28 offset:3072
	ds_read_b128 v[152:155], v80
	ds_read_b128 v[160:163], v80 offset:1024
	ds_read_b128 v[168:171], v80 offset:2048
	ds_read_b128 v[176:179], v80 offset:3072
	s_add_i32 s7, s4, 0xfff84000
	s_cmp_eq_u32 s6, 28
	s_cselect_b32 s17, s0, s7
	s_cselect_b32 s16, s1, s5
	s_or_b32 s7, s17, 0x4000
	ds_read_b128 v[192:195], v245
	ds_read_b128 v[196:199], v245 offset:1024
	ds_read_b128 v[200:203], v245 offset:2048
	ds_read_b128 v[204:207], v245 offset:3072
	ds_read_b128 v[220:223], v245 offset:4096
	ds_read_b128 v[224:227], v245 offset:5120
	ds_read_b128 v[228:231], v245 offset:6144
	ds_read_b128 v[246:249], v245 offset:7168
	s_mov_b32 m0, s79
	s_nop 0
	buffer_load_dwordx4 v242, s[24:27], s4 offen lds
	s_nop 0
	s_mov_b32 m0, s83
	s_nop 0
	buffer_load_dwordx4 v243, s[24:27], s4 offen lds
	s_waitcnt vmcnt(8)
	s_waitcnt lgkmcnt(0)
	s_barrier
	s_waitcnt lgkmcnt(7)
	v_mfma_f32_16x16x32_bf16 v[180:183], v[16:19], v[192:195], v[180:183]
	v_mfma_f32_16x16x32_bf16 v[164:167], v[24:27], v[192:195], v[164:167]
	s_waitcnt lgkmcnt(5)
	v_mfma_f32_16x16x32_bf16 v[148:151], v[16:19], v[200:203], v[148:151]
	v_mfma_f32_16x16x32_bf16 v[140:143], v[24:27], v[200:203], v[140:143]
	s_waitcnt lgkmcnt(3)
	v_mfma_f32_16x16x32_bf16 v[132:135], v[16:19], v[220:223], v[132:135]
	v_mfma_f32_16x16x32_bf16 v[124:127], v[24:27], v[220:223], v[124:127]
	s_waitcnt lgkmcnt(1)
	v_mfma_f32_16x16x32_bf16 v[116:119], v[16:19], v[228:231], v[116:119]
	v_mfma_f32_16x16x32_bf16 v[108:111], v[24:27], v[228:231], v[108:111]
	v_mfma_f32_16x16x32_bf16 v[180:183], v[20:23], v[196:199], v[180:183]
	v_mfma_f32_16x16x32_bf16 v[164:167], v[28:31], v[196:199], v[164:167]
	v_mfma_f32_16x16x32_bf16 v[148:151], v[20:23], v[204:207], v[148:151]
	v_mfma_f32_16x16x32_bf16 v[140:143], v[28:31], v[204:207], v[140:143]
	v_mfma_f32_16x16x32_bf16 v[132:135], v[20:23], v[224:227], v[132:135]
	v_mfma_f32_16x16x32_bf16 v[124:127], v[28:31], v[224:227], v[124:127]
	s_waitcnt lgkmcnt(0)
	v_mfma_f32_16x16x32_bf16 v[116:119], v[20:23], v[246:249], v[116:119]
	v_mfma_f32_16x16x32_bf16 v[108:111], v[28:31], v[246:249], v[108:111]
	v_mfma_f32_16x16x32_bf16 v[172:175], v[152:155], v[192:195], v[172:175]
	v_mfma_f32_16x16x32_bf16 v[156:159], v[168:171], v[192:195], v[156:159]
	v_mfma_f32_16x16x32_bf16 v[144:147], v[152:155], v[200:203], v[144:147]
	v_mfma_f32_16x16x32_bf16 v[136:139], v[168:171], v[200:203], v[136:139]
	v_mfma_f32_16x16x32_bf16 v[128:131], v[152:155], v[220:223], v[128:131]
	v_mfma_f32_16x16x32_bf16 v[120:123], v[168:171], v[220:223], v[120:123]
	v_mfma_f32_16x16x32_bf16 v[112:115], v[152:155], v[228:231], v[112:115]
	v_mfma_f32_16x16x32_bf16 v[104:107], v[168:171], v[228:231], v[104:107]
	v_mfma_f32_16x16x32_bf16 v[172:175], v[160:163], v[196:199], v[172:175]
	v_mfma_f32_16x16x32_bf16 v[156:159], v[176:179], v[196:199], v[156:159]
	v_mfma_f32_16x16x32_bf16 v[144:147], v[160:163], v[204:207], v[144:147]
	v_mfma_f32_16x16x32_bf16 v[136:139], v[176:179], v[204:207], v[136:139]
	v_mfma_f32_16x16x32_bf16 v[128:131], v[160:163], v[224:227], v[128:131]
	v_mfma_f32_16x16x32_bf16 v[120:123], v[176:179], v[224:227], v[120:123]
	v_mfma_f32_16x16x32_bf16 v[112:115], v[160:163], v[246:249], v[112:115]
	v_mfma_f32_16x16x32_bf16 v[104:107], v[176:179], v[246:249], v[104:107]
	s_barrier
	s_mov_b32 m0, s51
	s_nop 0
	buffer_load_dwordx4 v242, s[56:59], s16 offen lds
	s_add_i32 s18, s16, 0x80000
	s_mov_b32 m0, s52
	s_nop 0
	buffer_load_dwordx4 v243, s[56:59], s16 offen lds
	s_nop 0
	s_mov_b32 m0, s53
	s_nop 0
	buffer_load_dwordx4 v242, s[56:59], s18 offen lds
	s_nop 0
	s_mov_b32 m0, s55
	s_nop 0
	buffer_load_dwordx4 v243, s[56:59], s18 offen lds
	s_nop 0
	s_mov_b32 m0, s31
	s_nop 0
	buffer_load_dwordx4 v242, s[24:27], s17 offen lds
	s_nop 0
	s_mov_b32 m0, s68
	s_nop 0
	buffer_load_dwordx4 v243, s[24:27], s17 offen lds
	ds_read_b128 v[192:195], v245 offset:16384
	ds_read_b128 v[196:199], v245 offset:17408
	ds_read_b128 v[200:203], v245 offset:18432
	ds_read_b128 v[204:207], v245 offset:19456
	ds_read_b128 v[220:223], v245 offset:20480
	ds_read_b128 v[224:227], v245 offset:21504
	ds_read_b128 v[228:231], v245 offset:22528
	ds_read_b128 v[246:249], v245 offset:23552
	s_waitcnt vmcnt(8)
	s_waitcnt lgkmcnt(0)
	s_barrier
	s_waitcnt lgkmcnt(7)
	v_mfma_f32_16x16x32_bf16 v[76:79], v[16:19], v[192:195], v[76:79]
	v_mfma_f32_16x16x32_bf16 v[68:71], v[24:27], v[192:195], v[68:71]
	s_waitcnt lgkmcnt(5)
	v_mfma_f32_16x16x32_bf16 v[60:63], v[16:19], v[200:203], v[60:63]
	v_mfma_f32_16x16x32_bf16 v[52:55], v[24:27], v[200:203], v[52:55]
	s_waitcnt lgkmcnt(3)
	v_mfma_f32_16x16x32_bf16 v[44:47], v[16:19], v[220:223], v[44:47]
	v_mfma_f32_16x16x32_bf16 v[36:39], v[24:27], v[220:223], v[36:39]
	s_waitcnt lgkmcnt(1)
	v_mfma_f32_16x16x32_bf16 v[12:15], v[16:19], v[228:231], v[12:15]
	v_mfma_f32_16x16x32_bf16 v[4:7], v[24:27], v[228:231], v[4:7]
	v_mfma_f32_16x16x32_bf16 v[76:79], v[20:23], v[196:199], v[76:79]
	v_mfma_f32_16x16x32_bf16 v[68:71], v[28:31], v[196:199], v[68:71]
	v_mfma_f32_16x16x32_bf16 v[60:63], v[20:23], v[204:207], v[60:63]
	v_mfma_f32_16x16x32_bf16 v[52:55], v[28:31], v[204:207], v[52:55]
	v_mfma_f32_16x16x32_bf16 v[44:47], v[20:23], v[224:227], v[44:47]
	v_mfma_f32_16x16x32_bf16 v[36:39], v[28:31], v[224:227], v[36:39]
	s_waitcnt lgkmcnt(0)
	v_mfma_f32_16x16x32_bf16 v[12:15], v[20:23], v[246:249], v[12:15]
	v_mfma_f32_16x16x32_bf16 v[4:7], v[28:31], v[246:249], v[4:7]
	v_mfma_f32_16x16x32_bf16 v[40:43], v[152:155], v[220:223], v[40:43]
	v_mfma_f32_16x16x32_bf16 v[32:35], v[168:171], v[220:223], v[32:35]
	v_mfma_f32_16x16x32_bf16 v[8:11], v[152:155], v[228:231], v[8:11]
	v_mfma_f32_16x16x32_bf16 v[0:3], v[168:171], v[228:231], v[0:3]
	v_mfma_f32_16x16x32_bf16 v[16:19], v[152:155], v[192:195], v[72:75]
	v_mfma_f32_16x16x32_bf16 v[20:23], v[168:171], v[192:195], v[64:67]
	v_mfma_f32_16x16x32_bf16 v[24:27], v[152:155], v[200:203], v[56:59]
	v_mfma_f32_16x16x32_bf16 v[28:31], v[168:171], v[200:203], v[48:51]
	v_mfma_f32_16x16x32_bf16 v[40:43], v[160:163], v[224:227], v[40:43]
	v_mfma_f32_16x16x32_bf16 v[32:35], v[176:179], v[224:227], v[32:35]
	v_mfma_f32_16x16x32_bf16 v[8:11], v[160:163], v[246:249], v[8:11]
	v_mfma_f32_16x16x32_bf16 v[0:3], v[176:179], v[246:249], v[0:3]
	v_mfma_f32_16x16x32_bf16 v[16:19], v[160:163], v[196:199], v[16:19]
	v_mfma_f32_16x16x32_bf16 v[20:23], v[176:179], v[196:199], v[20:23]
	v_mfma_f32_16x16x32_bf16 v[24:27], v[160:163], v[204:207], v[24:27]
	v_mfma_f32_16x16x32_bf16 v[28:31], v[176:179], v[204:207], v[28:31]
	s_barrier
	s_add_i32 s17, s17, 0x80000
	s_mov_b32 m0, s69
	s_nop 0
	buffer_load_dwordx4 v242, s[24:27], s17 offen lds
	s_nop 0
	s_mov_b32 m0, s70
	s_nop 0
	buffer_load_dwordx4 v243, s[24:27], s17 offen lds
	v_add_u32_e32 v72, 0x18000, v83
	v_add_u32_e32 v80, 0x1c000, v83
	ds_read_b128 v[48:51], v72
	ds_read_b128 v[56:59], v72 offset:1024
	ds_read_b128 v[64:67], v72 offset:2048
	ds_read_b128 v[72:75], v72 offset:3072
	ds_read_b128 v[152:155], v80
	ds_read_b128 v[160:163], v80 offset:1024
	ds_read_b128 v[168:171], v80 offset:2048
	ds_read_b128 v[176:179], v80 offset:3072
	ds_read_b128 v[192:195], v245 offset:32768
	ds_read_b128 v[196:199], v245 offset:33792
	ds_read_b128 v[200:203], v245 offset:34816
	ds_read_b128 v[204:207], v245 offset:35840
	ds_read_b128 v[220:223], v245 offset:36864
	ds_read_b128 v[224:227], v245 offset:37888
	ds_read_b128 v[228:231], v245 offset:38912
	ds_read_b128 v[246:249], v245 offset:39936
	s_waitcnt vmcnt(8)
	s_waitcnt lgkmcnt(0)
	s_barrier
	s_waitcnt lgkmcnt(7)
	v_mfma_f32_16x16x32_bf16 v[180:183], v[48:51], v[192:195], v[180:183]
	v_mfma_f32_16x16x32_bf16 v[164:167], v[64:67], v[192:195], v[164:167]
	s_waitcnt lgkmcnt(5)
	v_mfma_f32_16x16x32_bf16 v[148:151], v[48:51], v[200:203], v[148:151]
	v_mfma_f32_16x16x32_bf16 v[140:143], v[64:67], v[200:203], v[140:143]
	s_waitcnt lgkmcnt(3)
	v_mfma_f32_16x16x32_bf16 v[132:135], v[48:51], v[220:223], v[132:135]
	v_mfma_f32_16x16x32_bf16 v[124:127], v[64:67], v[220:223], v[124:127]
	s_waitcnt lgkmcnt(1)
	v_mfma_f32_16x16x32_bf16 v[116:119], v[48:51], v[228:231], v[116:119]
	v_mfma_f32_16x16x32_bf16 v[108:111], v[64:67], v[228:231], v[108:111]
	v_mfma_f32_16x16x32_bf16 v[180:183], v[56:59], v[196:199], v[180:183]
	v_mfma_f32_16x16x32_bf16 v[164:167], v[72:75], v[196:199], v[164:167]
	v_mfma_f32_16x16x32_bf16 v[148:151], v[56:59], v[204:207], v[148:151]
	v_mfma_f32_16x16x32_bf16 v[140:143], v[72:75], v[204:207], v[140:143]
	v_mfma_f32_16x16x32_bf16 v[132:135], v[56:59], v[224:227], v[132:135]
	v_mfma_f32_16x16x32_bf16 v[124:127], v[72:75], v[224:227], v[124:127]
	s_waitcnt lgkmcnt(0)
	v_mfma_f32_16x16x32_bf16 v[116:119], v[56:59], v[246:249], v[116:119]
	v_mfma_f32_16x16x32_bf16 v[108:111], v[72:75], v[246:249], v[108:111]
	v_mfma_f32_16x16x32_bf16 v[172:175], v[152:155], v[192:195], v[172:175]
	v_mfma_f32_16x16x32_bf16 v[156:159], v[168:171], v[192:195], v[156:159]
	v_mfma_f32_16x16x32_bf16 v[144:147], v[152:155], v[200:203], v[144:147]
	v_mfma_f32_16x16x32_bf16 v[136:139], v[168:171], v[200:203], v[136:139]
	v_mfma_f32_16x16x32_bf16 v[128:131], v[152:155], v[220:223], v[128:131]
	v_mfma_f32_16x16x32_bf16 v[120:123], v[168:171], v[220:223], v[120:123]
	v_mfma_f32_16x16x32_bf16 v[112:115], v[152:155], v[228:231], v[112:115]
	v_mfma_f32_16x16x32_bf16 v[104:107], v[168:171], v[228:231], v[104:107]
	v_mfma_f32_16x16x32_bf16 v[172:175], v[160:163], v[196:199], v[172:175]
	v_mfma_f32_16x16x32_bf16 v[156:159], v[176:179], v[196:199], v[156:159]
	v_mfma_f32_16x16x32_bf16 v[144:147], v[160:163], v[204:207], v[144:147]
	v_mfma_f32_16x16x32_bf16 v[136:139], v[176:179], v[204:207], v[136:139]
	v_mfma_f32_16x16x32_bf16 v[128:131], v[160:163], v[224:227], v[128:131]
	v_mfma_f32_16x16x32_bf16 v[120:123], v[176:179], v[224:227], v[120:123]
	v_mfma_f32_16x16x32_bf16 v[112:115], v[160:163], v[246:249], v[112:115]
	v_mfma_f32_16x16x32_bf16 v[104:107], v[176:179], v[246:249], v[104:107]
	s_barrier
	s_or_b32 s17, s16, 0x4000
	s_mov_b32 m0, s73
	s_nop 0
	buffer_load_dwordx4 v242, s[56:59], s17 offen lds
	s_add_i32 s16, s16, 0x84000
	s_mov_b32 m0, s74
	s_nop 0
	buffer_load_dwordx4 v243, s[56:59], s17 offen lds
	s_nop 0
	s_mov_b32 m0, s77
	s_nop 0
	buffer_load_dwordx4 v242, s[56:59], s16 offen lds
	s_nop 0
	s_mov_b32 m0, s78
	s_nop 0
	buffer_load_dwordx4 v243, s[56:59], s16 offen lds
	s_nop 0
	s_mov_b32 m0, s75
	s_nop 0
	buffer_load_dwordx4 v242, s[24:27], s7 offen lds
	s_nop 0
	s_mov_b32 m0, s76
	s_nop 0
	buffer_load_dwordx4 v243, s[24:27], s7 offen lds
	ds_read_b128 v[192:195], v245 offset:49152
	ds_read_b128 v[196:199], v245 offset:50176
	ds_read_b128 v[200:203], v245 offset:51200
	ds_read_b128 v[204:207], v245 offset:52224
	ds_read_b128 v[220:223], v245 offset:53248
	ds_read_b128 v[224:227], v245 offset:54272
	ds_read_b128 v[228:231], v245 offset:55296
	ds_read_b128 v[246:249], v245 offset:56320
	s_waitcnt vmcnt(8)
	s_waitcnt lgkmcnt(0)
	s_barrier
	s_waitcnt lgkmcnt(7)
	v_mfma_f32_16x16x32_bf16 v[76:79], v[48:51], v[192:195], v[76:79]
	v_mfma_f32_16x16x32_bf16 v[68:71], v[64:67], v[192:195], v[68:71]
	s_waitcnt lgkmcnt(5)
	v_mfma_f32_16x16x32_bf16 v[60:63], v[48:51], v[200:203], v[60:63]
	v_mfma_f32_16x16x32_bf16 v[52:55], v[64:67], v[200:203], v[52:55]
	s_waitcnt lgkmcnt(3)
	v_mfma_f32_16x16x32_bf16 v[44:47], v[48:51], v[220:223], v[44:47]
	v_mfma_f32_16x16x32_bf16 v[36:39], v[64:67], v[220:223], v[36:39]
	s_waitcnt lgkmcnt(1)
	v_mfma_f32_16x16x32_bf16 v[12:15], v[48:51], v[228:231], v[12:15]
	v_mfma_f32_16x16x32_bf16 v[4:7], v[64:67], v[228:231], v[4:7]
	v_mfma_f32_16x16x32_bf16 v[76:79], v[56:59], v[196:199], v[76:79]
	v_mfma_f32_16x16x32_bf16 v[68:71], v[72:75], v[196:199], v[68:71]
	v_mfma_f32_16x16x32_bf16 v[60:63], v[56:59], v[204:207], v[60:63]
	v_mfma_f32_16x16x32_bf16 v[52:55], v[72:75], v[204:207], v[52:55]
	v_mfma_f32_16x16x32_bf16 v[44:47], v[56:59], v[224:227], v[44:47]
	v_mfma_f32_16x16x32_bf16 v[36:39], v[72:75], v[224:227], v[36:39]
	s_waitcnt lgkmcnt(0)
	v_mfma_f32_16x16x32_bf16 v[12:15], v[56:59], v[246:249], v[12:15]
	v_mfma_f32_16x16x32_bf16 v[4:7], v[72:75], v[246:249], v[4:7]
	v_mfma_f32_16x16x32_bf16 v[16:19], v[152:155], v[192:195], v[16:19]
	v_mfma_f32_16x16x32_bf16 v[72:75], v[160:163], v[196:199], v[16:19]
	v_mfma_f32_16x16x32_bf16 v[16:19], v[168:171], v[192:195], v[20:23]
	v_mfma_f32_16x16x32_bf16 v[64:67], v[176:179], v[196:199], v[16:19]
	v_mfma_f32_16x16x32_bf16 v[16:19], v[152:155], v[200:203], v[24:27]
	v_mfma_f32_16x16x32_bf16 v[56:59], v[160:163], v[204:207], v[16:19]
	v_mfma_f32_16x16x32_bf16 v[16:19], v[168:171], v[200:203], v[28:31]
	v_mfma_f32_16x16x32_bf16 v[48:51], v[176:179], v[204:207], v[16:19]
	v_mfma_f32_16x16x32_bf16 v[16:19], v[152:155], v[220:223], v[40:43]
	v_mfma_f32_16x16x32_bf16 v[40:43], v[160:163], v[224:227], v[16:19]
	v_mfma_f32_16x16x32_bf16 v[16:19], v[168:171], v[220:223], v[32:35]
	v_mfma_f32_16x16x32_bf16 v[8:11], v[152:155], v[228:231], v[8:11]
	v_mfma_f32_16x16x32_bf16 v[0:3], v[168:171], v[228:231], v[0:3]
	v_mfma_f32_16x16x32_bf16 v[32:35], v[176:179], v[224:227], v[16:19]
	v_mfma_f32_16x16x32_bf16 v[8:11], v[160:163], v[246:249], v[8:11]
	v_mfma_f32_16x16x32_bf16 v[0:3], v[176:179], v[246:249], v[0:3]
	s_barrier
	s_add_i32 s6, s6, 2
	s_add_i32 s4, s4, 0x8000
	s_add_i32 s5, s5, 0x8000
	s_cmp_gt_u32 s6, 29
	s_cbranch_scc0 .LBB0_143

.LBB0_594:
	v_add_u32_e32 v80, 0x10000, v226
	ds_read_b128 v[152:155], v80
	ds_read_b128 v[156:159], v80 offset:1024
	ds_read_b128 v[160:163], v80 offset:2048
	ds_read_b128 v[164:167], v80 offset:3072
	v_add_u32_e32 v80, 0x14000, v226
	ds_read_b128 v[168:171], v80
	ds_read_b128 v[172:175], v80 offset:1024
	ds_read_b128 v[176:179], v80 offset:2048
	ds_read_b128 v[180:183], v80 offset:3072
	s_add_i32 s97, s96, s39
	s_add_i32 s94, s97, 0x8000
	s_add_i32 s95, s93, s39
	s_cmp_eq_u32 s39, 0x78000
	s_cselect_b32 s36, vcc_lo, s94
	s_cselect_b32 s95, vcc_hi, s95
	s_or_b32 s94, s36, 0x4000
	ds_read_b128 v[184:187], v227
	ds_read_b128 v[188:191], v227 offset:1024
	ds_read_b128 v[192:195], v227 offset:2048
	ds_read_b128 v[196:199], v227 offset:3072
	ds_read_b128 v[200:203], v227 offset:4096
	ds_read_b128 v[204:207], v227 offset:5120
	ds_read_b128 v[228:231], v227 offset:6144
	ds_read_b128 v[240:243], v227 offset:7168
	s_add_i32 s97, s97, 0x84000
	s_mov_b32 m0, s85
	s_nop 0
	buffer_load_dwordx4 v224, s[60:63], s97 offen lds
	s_nop 0
	s_mov_b32 m0, s86
	s_nop 0
	buffer_load_dwordx4 v225, s[60:63], s97 offen lds
	s_waitcnt vmcnt(8)
	s_waitcnt lgkmcnt(0)
	s_barrier
	s_waitcnt lgkmcnt(7)
	v_mfma_f32_16x16x32_bf16 v[148:151], v[152:155], v[184:187], v[148:151]
	v_mfma_f32_16x16x32_bf16 v[144:147], v[160:163], v[184:187], v[144:147]
	s_waitcnt lgkmcnt(5)
	v_mfma_f32_16x16x32_bf16 v[132:135], v[152:155], v[192:195], v[132:135]
	v_mfma_f32_16x16x32_bf16 v[128:131], v[160:163], v[192:195], v[128:131]
	s_waitcnt lgkmcnt(3)
	v_mfma_f32_16x16x32_bf16 v[116:119], v[152:155], v[200:203], v[116:119]
	v_mfma_f32_16x16x32_bf16 v[112:115], v[160:163], v[200:203], v[112:115]
	s_waitcnt lgkmcnt(1)
	v_mfma_f32_16x16x32_bf16 v[76:79], v[152:155], v[228:231], v[76:79]
	v_mfma_f32_16x16x32_bf16 v[72:75], v[160:163], v[228:231], v[72:75]
	v_mfma_f32_16x16x32_bf16 v[148:151], v[156:159], v[188:191], v[148:151]
	v_mfma_f32_16x16x32_bf16 v[144:147], v[164:167], v[188:191], v[144:147]
	v_mfma_f32_16x16x32_bf16 v[132:135], v[156:159], v[196:199], v[132:135]
	v_mfma_f32_16x16x32_bf16 v[128:131], v[164:167], v[196:199], v[128:131]
	v_mfma_f32_16x16x32_bf16 v[116:119], v[156:159], v[204:207], v[116:119]
	v_mfma_f32_16x16x32_bf16 v[112:115], v[164:167], v[204:207], v[112:115]
	s_waitcnt lgkmcnt(0)
	v_mfma_f32_16x16x32_bf16 v[76:79], v[156:159], v[240:243], v[76:79]
	v_mfma_f32_16x16x32_bf16 v[72:75], v[164:167], v[240:243], v[72:75]
	v_mfma_f32_16x16x32_bf16 v[140:143], v[168:171], v[184:187], v[140:143]
	v_mfma_f32_16x16x32_bf16 v[136:139], v[176:179], v[184:187], v[136:139]
	v_mfma_f32_16x16x32_bf16 v[124:127], v[168:171], v[192:195], v[124:127]
	v_mfma_f32_16x16x32_bf16 v[120:123], v[176:179], v[192:195], v[120:123]
	v_mfma_f32_16x16x32_bf16 v[108:111], v[168:171], v[200:203], v[108:111]
	v_mfma_f32_16x16x32_bf16 v[104:107], v[176:179], v[200:203], v[104:107]
	v_mfma_f32_16x16x32_bf16 v[68:71], v[168:171], v[228:231], v[68:71]
	v_mfma_f32_16x16x32_bf16 v[64:67], v[176:179], v[228:231], v[64:67]
	v_mfma_f32_16x16x32_bf16 v[140:143], v[172:175], v[188:191], v[140:143]
	v_mfma_f32_16x16x32_bf16 v[136:139], v[180:183], v[188:191], v[136:139]
	v_mfma_f32_16x16x32_bf16 v[124:127], v[172:175], v[196:199], v[124:127]
	v_mfma_f32_16x16x32_bf16 v[120:123], v[180:183], v[196:199], v[120:123]
	v_mfma_f32_16x16x32_bf16 v[108:111], v[172:175], v[204:207], v[108:111]
	v_mfma_f32_16x16x32_bf16 v[104:107], v[180:183], v[204:207], v[104:107]
	v_mfma_f32_16x16x32_bf16 v[68:71], v[172:175], v[240:243], v[68:71]
	v_mfma_f32_16x16x32_bf16 v[64:67], v[180:183], v[240:243], v[64:67]
	s_barrier
	s_mov_b32 m0, s34
	s_nop 0
	buffer_load_dwordx4 v224, s[48:51], s95 offen lds
	s_add_i32 s97, s95, 0x80000
	s_mov_b32 m0, s55
	s_nop 0
	buffer_load_dwordx4 v225, s[48:51], s95 offen lds
	s_nop 0
	s_mov_b32 m0, s72
	s_nop 0
	buffer_load_dwordx4 v224, s[48:51], s97 offen lds
	s_nop 0
	s_mov_b32 m0, s73
	s_nop 0
	buffer_load_dwordx4 v225, s[48:51], s97 offen lds
	s_nop 0
	s_mov_b32 m0, s31
	s_nop 0
	buffer_load_dwordx4 v224, s[60:63], s36 offen lds
	s_nop 0
	s_mov_b32 m0, s74
	s_nop 0
	buffer_load_dwordx4 v225, s[60:63], s36 offen lds
	ds_read_b128 v[184:187], v227 offset:16384
	ds_read_b128 v[188:191], v227 offset:17408
	ds_read_b128 v[192:195], v227 offset:18432
	ds_read_b128 v[196:199], v227 offset:19456
	ds_read_b128 v[200:203], v227 offset:20480
	ds_read_b128 v[204:207], v227 offset:21504
	ds_read_b128 v[228:231], v227 offset:22528
	ds_read_b128 v[240:243], v227 offset:23552
	s_waitcnt vmcnt(8)
	s_waitcnt lgkmcnt(0)
	s_barrier
	s_waitcnt lgkmcnt(7)
	v_mfma_f32_16x16x32_bf16 v[60:63], v[152:155], v[184:187], v[60:63]
	v_mfma_f32_16x16x32_bf16 v[56:59], v[160:163], v[184:187], v[56:59]
	s_waitcnt lgkmcnt(5)
	v_mfma_f32_16x16x32_bf16 v[44:47], v[152:155], v[192:195], v[44:47]
	v_mfma_f32_16x16x32_bf16 v[40:43], v[160:163], v[192:195], v[40:43]
	s_waitcnt lgkmcnt(3)
	v_mfma_f32_16x16x32_bf16 v[28:31], v[152:155], v[200:203], v[28:31]
	v_mfma_f32_16x16x32_bf16 v[24:27], v[160:163], v[200:203], v[24:27]
	s_waitcnt lgkmcnt(1)
	v_mfma_f32_16x16x32_bf16 v[12:15], v[152:155], v[228:231], v[12:15]
	v_mfma_f32_16x16x32_bf16 v[8:11], v[160:163], v[228:231], v[8:11]
	v_mfma_f32_16x16x32_bf16 v[60:63], v[156:159], v[188:191], v[60:63]
	v_mfma_f32_16x16x32_bf16 v[56:59], v[164:167], v[188:191], v[56:59]
	v_mfma_f32_16x16x32_bf16 v[44:47], v[156:159], v[196:199], v[44:47]
	v_mfma_f32_16x16x32_bf16 v[40:43], v[164:167], v[196:199], v[40:43]
	v_mfma_f32_16x16x32_bf16 v[28:31], v[156:159], v[204:207], v[28:31]
	v_mfma_f32_16x16x32_bf16 v[24:27], v[164:167], v[204:207], v[24:27]
	s_waitcnt lgkmcnt(0)
	v_mfma_f32_16x16x32_bf16 v[12:15], v[156:159], v[240:243], v[12:15]
	v_mfma_f32_16x16x32_bf16 v[8:11], v[164:167], v[240:243], v[8:11]
	v_mfma_f32_16x16x32_bf16 v[52:55], v[168:171], v[184:187], v[52:55]
	v_mfma_f32_16x16x32_bf16 v[48:51], v[176:179], v[184:187], v[48:51]
	v_mfma_f32_16x16x32_bf16 v[36:39], v[168:171], v[192:195], v[36:39]
	v_mfma_f32_16x16x32_bf16 v[32:35], v[176:179], v[192:195], v[32:35]
	v_mfma_f32_16x16x32_bf16 v[20:23], v[168:171], v[200:203], v[20:23]
	v_mfma_f32_16x16x32_bf16 v[16:19], v[176:179], v[200:203], v[16:19]
	v_mfma_f32_16x16x32_bf16 v[4:7], v[168:171], v[228:231], v[4:7]
	v_mfma_f32_16x16x32_bf16 v[0:3], v[176:179], v[228:231], v[0:3]
	v_mfma_f32_16x16x32_bf16 v[52:55], v[172:175], v[188:191], v[52:55]
	v_mfma_f32_16x16x32_bf16 v[48:51], v[180:183], v[188:191], v[48:51]
	v_mfma_f32_16x16x32_bf16 v[36:39], v[172:175], v[196:199], v[36:39]
	v_mfma_f32_16x16x32_bf16 v[32:35], v[180:183], v[196:199], v[32:35]
	v_mfma_f32_16x16x32_bf16 v[20:23], v[172:175], v[204:207], v[20:23]
	v_mfma_f32_16x16x32_bf16 v[16:19], v[180:183], v[204:207], v[16:19]
	v_mfma_f32_16x16x32_bf16 v[4:7], v[172:175], v[240:243], v[4:7]
	v_mfma_f32_16x16x32_bf16 v[0:3], v[180:183], v[240:243], v[0:3]
	s_barrier
	s_add_i32 s36, s36, 0x80000
	s_mov_b32 m0, s75
	s_nop 0
	buffer_load_dwordx4 v224, s[60:63], s36 offen lds
	s_nop 0
	s_mov_b32 m0, s76
	s_nop 0
	buffer_load_dwordx4 v225, s[60:63], s36 offen lds
	v_add_u32_e32 v80, 0x18000, v226
	ds_read_b128 v[152:155], v80
	ds_read_b128 v[156:159], v80 offset:1024
	ds_read_b128 v[160:163], v80 offset:2048
	ds_read_b128 v[164:167], v80 offset:3072
	v_add_u32_e32 v80, 0x1c000, v226
	ds_read_b128 v[168:171], v80
	ds_read_b128 v[172:175], v80 offset:1024
	ds_read_b128 v[176:179], v80 offset:2048
	ds_read_b128 v[180:183], v80 offset:3072
	ds_read_b128 v[184:187], v227 offset:32768
	ds_read_b128 v[188:191], v227 offset:33792
	ds_read_b128 v[192:195], v227 offset:34816
	ds_read_b128 v[196:199], v227 offset:35840
	ds_read_b128 v[200:203], v227 offset:36864
	ds_read_b128 v[204:207], v227 offset:37888
	ds_read_b128 v[228:231], v227 offset:38912
	ds_read_b128 v[240:243], v227 offset:39936
	s_waitcnt vmcnt(8)
	s_waitcnt lgkmcnt(0)
	s_barrier
	s_waitcnt lgkmcnt(7)
	v_mfma_f32_16x16x32_bf16 v[148:151], v[152:155], v[184:187], v[148:151]
	v_mfma_f32_16x16x32_bf16 v[144:147], v[160:163], v[184:187], v[144:147]
	s_waitcnt lgkmcnt(5)
	v_mfma_f32_16x16x32_bf16 v[132:135], v[152:155], v[192:195], v[132:135]
	v_mfma_f32_16x16x32_bf16 v[128:131], v[160:163], v[192:195], v[128:131]
	s_waitcnt lgkmcnt(3)
	v_mfma_f32_16x16x32_bf16 v[116:119], v[152:155], v[200:203], v[116:119]
	v_mfma_f32_16x16x32_bf16 v[112:115], v[160:163], v[200:203], v[112:115]
	s_waitcnt lgkmcnt(1)
	v_mfma_f32_16x16x32_bf16 v[76:79], v[152:155], v[228:231], v[76:79]
	v_mfma_f32_16x16x32_bf16 v[72:75], v[160:163], v[228:231], v[72:75]
	v_mfma_f32_16x16x32_bf16 v[148:151], v[156:159], v[188:191], v[148:151]
	v_mfma_f32_16x16x32_bf16 v[144:147], v[164:167], v[188:191], v[144:147]
	v_mfma_f32_16x16x32_bf16 v[132:135], v[156:159], v[196:199], v[132:135]
	v_mfma_f32_16x16x32_bf16 v[128:131], v[164:167], v[196:199], v[128:131]
	v_mfma_f32_16x16x32_bf16 v[116:119], v[156:159], v[204:207], v[116:119]
	v_mfma_f32_16x16x32_bf16 v[112:115], v[164:167], v[204:207], v[112:115]
	s_waitcnt lgkmcnt(0)
	v_mfma_f32_16x16x32_bf16 v[76:79], v[156:159], v[240:243], v[76:79]
	v_mfma_f32_16x16x32_bf16 v[72:75], v[164:167], v[240:243], v[72:75]
	v_mfma_f32_16x16x32_bf16 v[140:143], v[168:171], v[184:187], v[140:143]
	v_mfma_f32_16x16x32_bf16 v[136:139], v[176:179], v[184:187], v[136:139]
	v_mfma_f32_16x16x32_bf16 v[124:127], v[168:171], v[192:195], v[124:127]
	v_mfma_f32_16x16x32_bf16 v[120:123], v[176:179], v[192:195], v[120:123]
	v_mfma_f32_16x16x32_bf16 v[108:111], v[168:171], v[200:203], v[108:111]
	v_mfma_f32_16x16x32_bf16 v[104:107], v[176:179], v[200:203], v[104:107]
	v_mfma_f32_16x16x32_bf16 v[68:71], v[168:171], v[228:231], v[68:71]
	v_mfma_f32_16x16x32_bf16 v[64:67], v[176:179], v[228:231], v[64:67]
	v_mfma_f32_16x16x32_bf16 v[140:143], v[172:175], v[188:191], v[140:143]
	v_mfma_f32_16x16x32_bf16 v[136:139], v[180:183], v[188:191], v[136:139]
	v_mfma_f32_16x16x32_bf16 v[124:127], v[172:175], v[196:199], v[124:127]
	v_mfma_f32_16x16x32_bf16 v[120:123], v[180:183], v[196:199], v[120:123]
	v_mfma_f32_16x16x32_bf16 v[108:111], v[172:175], v[204:207], v[108:111]
	v_mfma_f32_16x16x32_bf16 v[104:107], v[180:183], v[204:207], v[104:107]
	v_mfma_f32_16x16x32_bf16 v[68:71], v[172:175], v[240:243], v[68:71]
	v_mfma_f32_16x16x32_bf16 v[64:67], v[180:183], v[240:243], v[64:67]
	s_barrier
	s_or_b32 s36, s95, 0x4000
	s_mov_b32 m0, s77
	s_nop 0
	buffer_load_dwordx4 v224, s[48:51], s36 offen lds
	s_nop 0
	s_mov_b32 m0, s78
	s_nop 0
	buffer_load_dwordx4 v225, s[48:51], s36 offen lds
	s_add_i32 s36, s95, 0x84000
	s_mov_b32 m0, s83
	s_nop 0
	buffer_load_dwordx4 v224, s[48:51], s36 offen lds
	s_nop 0
	s_mov_b32 m0, s84
	s_nop 0
	buffer_load_dwordx4 v225, s[48:51], s36 offen lds
	s_nop 0
	s_mov_b32 m0, s79
	s_nop 0
	buffer_load_dwordx4 v224, s[60:63], s94 offen lds
	s_nop 0
	s_mov_b32 m0, s82
	s_nop 0
	buffer_load_dwordx4 v225, s[60:63], s94 offen lds
	ds_read_b128 v[184:187], v227 offset:49152
	ds_read_b128 v[188:191], v227 offset:50176
	ds_read_b128 v[192:195], v227 offset:51200
	ds_read_b128 v[196:199], v227 offset:52224
	ds_read_b128 v[200:203], v227 offset:53248
	ds_read_b128 v[204:207], v227 offset:54272
	ds_read_b128 v[228:231], v227 offset:55296
	ds_read_b128 v[240:243], v227 offset:56320
	s_waitcnt vmcnt(8)
	s_waitcnt lgkmcnt(0)
	s_barrier
	s_waitcnt lgkmcnt(7)
	v_mfma_f32_16x16x32_bf16 v[60:63], v[152:155], v[184:187], v[60:63]
	v_mfma_f32_16x16x32_bf16 v[56:59], v[160:163], v[184:187], v[56:59]
	s_waitcnt lgkmcnt(5)
	v_mfma_f32_16x16x32_bf16 v[44:47], v[152:155], v[192:195], v[44:47]
	v_mfma_f32_16x16x32_bf16 v[40:43], v[160:163], v[192:195], v[40:43]
	s_waitcnt lgkmcnt(3)
	v_mfma_f32_16x16x32_bf16 v[28:31], v[152:155], v[200:203], v[28:31]
	v_mfma_f32_16x16x32_bf16 v[24:27], v[160:163], v[200:203], v[24:27]
	s_waitcnt lgkmcnt(1)
	v_mfma_f32_16x16x32_bf16 v[12:15], v[152:155], v[228:231], v[12:15]
	v_mfma_f32_16x16x32_bf16 v[8:11], v[160:163], v[228:231], v[8:11]
	v_mfma_f32_16x16x32_bf16 v[60:63], v[156:159], v[188:191], v[60:63]
	v_mfma_f32_16x16x32_bf16 v[56:59], v[164:167], v[188:191], v[56:59]
	v_mfma_f32_16x16x32_bf16 v[44:47], v[156:159], v[196:199], v[44:47]
	v_mfma_f32_16x16x32_bf16 v[40:43], v[164:167], v[196:199], v[40:43]
	v_mfma_f32_16x16x32_bf16 v[28:31], v[156:159], v[204:207], v[28:31]
	v_mfma_f32_16x16x32_bf16 v[24:27], v[164:167], v[204:207], v[24:27]
	s_waitcnt lgkmcnt(0)
	v_mfma_f32_16x16x32_bf16 v[12:15], v[156:159], v[240:243], v[12:15]
	v_mfma_f32_16x16x32_bf16 v[8:11], v[164:167], v[240:243], v[8:11]
	v_mfma_f32_16x16x32_bf16 v[52:55], v[168:171], v[184:187], v[52:55]
	v_mfma_f32_16x16x32_bf16 v[48:51], v[176:179], v[184:187], v[48:51]
	v_mfma_f32_16x16x32_bf16 v[36:39], v[168:171], v[192:195], v[36:39]
	v_mfma_f32_16x16x32_bf16 v[32:35], v[176:179], v[192:195], v[32:35]
	v_mfma_f32_16x16x32_bf16 v[20:23], v[168:171], v[200:203], v[20:23]
	v_mfma_f32_16x16x32_bf16 v[16:19], v[176:179], v[200:203], v[16:19]
	v_mfma_f32_16x16x32_bf16 v[4:7], v[168:171], v[228:231], v[4:7]
	v_mfma_f32_16x16x32_bf16 v[0:3], v[176:179], v[228:231], v[0:3]
	v_mfma_f32_16x16x32_bf16 v[52:55], v[172:175], v[188:191], v[52:55]
	v_mfma_f32_16x16x32_bf16 v[48:51], v[180:183], v[188:191], v[48:51]
	v_mfma_f32_16x16x32_bf16 v[36:39], v[172:175], v[196:199], v[36:39]
	v_mfma_f32_16x16x32_bf16 v[32:35], v[180:183], v[196:199], v[32:35]
	v_mfma_f32_16x16x32_bf16 v[20:23], v[172:175], v[204:207], v[20:23]
	v_mfma_f32_16x16x32_bf16 v[16:19], v[180:183], v[204:207], v[16:19]
	v_mfma_f32_16x16x32_bf16 v[4:7], v[172:175], v[240:243], v[4:7]
	v_mfma_f32_16x16x32_bf16 v[0:3], v[180:183], v[240:243], v[0:3]
	s_barrier
	s_add_i32 s38, s38, 2
	s_add_i32 s39, s39, 0x8000
	s_cmp_gt_u32 s38, 29
	s_cbranch_scc1 .LBB0_597

.Lnb_p4:
	s_add_i32 s11, s8, 0xfff84000
	s_cmp_eq_u32 s10, 28
	s_cselect_b32 s13, s6, s11
	s_cselect_b32 s12, s7, s9
	s_or_b32 s11, s13, 0x4000
	s_mov_b32 m0, s89
	s_nop 0
	buffer_load_dwordx4 v220, s[64:67], s8 offen lds
	s_nop 0
	s_mov_b32 m0, s91
	s_nop 0
	buffer_load_dwordx4 v221, s[64:67], s8 offen lds
	s_waitcnt vmcnt(24)
	s_waitcnt lgkmcnt(0)
	s_barrier
	s_waitcnt lgkmcnt(7)
	v_mfma_f32_16x16x32_bf16 v[164:167], v[128:131], v[184:187], 0
	v_mfma_f32_16x16x32_bf16 v[160:163], v[152:155], v[184:187], 0
	s_waitcnt lgkmcnt(5)
	v_mfma_f32_16x16x32_bf16 v[136:139], v[128:131], v[192:195], 0
	v_mfma_f32_16x16x32_bf16 v[132:135], v[152:155], v[192:195], 0
	s_waitcnt lgkmcnt(3)
	v_mfma_f32_16x16x32_bf16 v[116:119], v[128:131], v[200:203], 0
	v_mfma_f32_16x16x32_bf16 v[112:115], v[152:155], v[200:203], 0
	s_waitcnt lgkmcnt(1)
	v_mfma_f32_16x16x32_bf16 v[76:79], v[128:131], v[224:227], 0
	v_mfma_f32_16x16x32_bf16 v[72:75], v[152:155], v[224:227], 0
	v_mfma_f32_16x16x32_bf16 v[164:167], v[140:143], v[188:191], v[164:167]
	v_mfma_f32_16x16x32_bf16 v[160:163], v[156:159], v[188:191], v[160:163]
	v_mfma_f32_16x16x32_bf16 v[136:139], v[140:143], v[196:199], v[136:139]
	v_mfma_f32_16x16x32_bf16 v[132:135], v[156:159], v[196:199], v[132:135]
	v_mfma_f32_16x16x32_bf16 v[116:119], v[140:143], v[204:207], v[116:119]
	v_mfma_f32_16x16x32_bf16 v[112:115], v[156:159], v[204:207], v[112:115]
	s_waitcnt lgkmcnt(0)
	v_mfma_f32_16x16x32_bf16 v[76:79], v[140:143], v[228:231], v[76:79]
	v_mfma_f32_16x16x32_bf16 v[72:75], v[156:159], v[228:231], v[72:75]
	v_mfma_f32_16x16x32_bf16 v[148:151], v[168:171], v[184:187], 0
	v_mfma_f32_16x16x32_bf16 v[144:147], v[176:179], v[184:187], 0
	v_mfma_f32_16x16x32_bf16 v[124:127], v[168:171], v[192:195], 0
	v_mfma_f32_16x16x32_bf16 v[120:123], v[176:179], v[192:195], 0
	v_mfma_f32_16x16x32_bf16 v[108:111], v[168:171], v[200:203], 0
	v_mfma_f32_16x16x32_bf16 v[104:107], v[176:179], v[200:203], 0
	v_mfma_f32_16x16x32_bf16 v[68:71], v[168:171], v[224:227], 0
	v_mfma_f32_16x16x32_bf16 v[64:67], v[176:179], v[224:227], 0
	v_mfma_f32_16x16x32_bf16 v[148:151], v[172:175], v[188:191], v[148:151]
	v_mfma_f32_16x16x32_bf16 v[144:147], v[180:183], v[188:191], v[144:147]
	v_mfma_f32_16x16x32_bf16 v[124:127], v[172:175], v[196:199], v[124:127]
	v_mfma_f32_16x16x32_bf16 v[120:123], v[180:183], v[196:199], v[120:123]
	v_mfma_f32_16x16x32_bf16 v[108:111], v[172:175], v[204:207], v[108:111]
	v_mfma_f32_16x16x32_bf16 v[104:107], v[180:183], v[204:207], v[104:107]
	v_mfma_f32_16x16x32_bf16 v[68:71], v[172:175], v[228:231], v[68:71]
	v_mfma_f32_16x16x32_bf16 v[64:67], v[180:183], v[228:231], v[64:67]
	s_barrier
	s_mov_b32 m0, s55
	s_nop 0
	buffer_load_dwordx4 v220, s[48:51], s12 offen lds
	s_add_i32 s14, s12, 0x80000
	s_mov_b32 m0, s76
	s_nop 0
	buffer_load_dwordx4 v221, s[48:51], s12 offen lds
	s_nop 0
	s_mov_b32 m0, s77
	s_nop 0
	buffer_load_dwordx4 v220, s[48:51], s14 offen lds
	s_nop 0
	s_mov_b32 m0, s78
	s_nop 0
	buffer_load_dwordx4 v221, s[48:51], s14 offen lds
	s_nop 0
	s_mov_b32 m0, s31
	s_nop 0
	buffer_load_dwordx4 v220, s[64:67], s13 offen lds
	s_nop 0
	s_mov_b32 m0, s79
	s_nop 0
	buffer_load_dwordx4 v221, s[64:67], s13 offen lds
	ds_read_b128 v[184:187], v223 offset:16384
	ds_read_b128 v[188:191], v223 offset:17408
	ds_read_b128 v[192:195], v223 offset:18432
	ds_read_b128 v[196:199], v223 offset:19456
	ds_read_b128 v[200:203], v223 offset:20480
	ds_read_b128 v[204:207], v223 offset:21504
	ds_read_b128 v[224:227], v223 offset:22528
	ds_read_b128 v[228:231], v223 offset:23552
	s_waitcnt vmcnt(24)
	s_waitcnt lgkmcnt(0)
	s_barrier
	s_waitcnt lgkmcnt(7)
	v_mfma_f32_16x16x32_bf16 v[60:63], v[128:131], v[184:187], 0
	v_mfma_f32_16x16x32_bf16 v[56:59], v[152:155], v[184:187], 0
	s_waitcnt lgkmcnt(5)
	v_mfma_f32_16x16x32_bf16 v[44:47], v[128:131], v[192:195], 0
	v_mfma_f32_16x16x32_bf16 v[40:43], v[152:155], v[192:195], 0
	s_waitcnt lgkmcnt(3)
	v_mfma_f32_16x16x32_bf16 v[28:31], v[128:131], v[200:203], 0
	v_mfma_f32_16x16x32_bf16 v[24:27], v[152:155], v[200:203], 0
	s_waitcnt lgkmcnt(1)
	v_mfma_f32_16x16x32_bf16 v[12:15], v[128:131], v[224:227], 0
	v_mfma_f32_16x16x32_bf16 v[8:11], v[152:155], v[224:227], 0
	v_mfma_f32_16x16x32_bf16 v[60:63], v[140:143], v[188:191], v[60:63]
	v_mfma_f32_16x16x32_bf16 v[56:59], v[156:159], v[188:191], v[56:59]
	v_mfma_f32_16x16x32_bf16 v[44:47], v[140:143], v[196:199], v[44:47]
	v_mfma_f32_16x16x32_bf16 v[40:43], v[156:159], v[196:199], v[40:43]
	v_mfma_f32_16x16x32_bf16 v[28:31], v[140:143], v[204:207], v[28:31]
	v_mfma_f32_16x16x32_bf16 v[24:27], v[156:159], v[204:207], v[24:27]
	s_waitcnt lgkmcnt(0)
	v_mfma_f32_16x16x32_bf16 v[12:15], v[140:143], v[228:231], v[12:15]
	v_mfma_f32_16x16x32_bf16 v[8:11], v[156:159], v[228:231], v[8:11]
	v_mfma_f32_16x16x32_bf16 v[52:55], v[168:171], v[184:187], 0
	v_mfma_f32_16x16x32_bf16 v[48:51], v[176:179], v[184:187], 0
	v_mfma_f32_16x16x32_bf16 v[36:39], v[168:171], v[192:195], 0
	v_mfma_f32_16x16x32_bf16 v[32:35], v[176:179], v[192:195], 0
	v_mfma_f32_16x16x32_bf16 v[20:23], v[168:171], v[200:203], 0
	v_mfma_f32_16x16x32_bf16 v[16:19], v[176:179], v[200:203], 0
	v_mfma_f32_16x16x32_bf16 v[4:7], v[168:171], v[224:227], 0
	v_mfma_f32_16x16x32_bf16 v[0:3], v[176:179], v[224:227], 0
	v_mfma_f32_16x16x32_bf16 v[52:55], v[172:175], v[188:191], v[52:55]
	v_mfma_f32_16x16x32_bf16 v[48:51], v[180:183], v[188:191], v[48:51]
	v_mfma_f32_16x16x32_bf16 v[36:39], v[172:175], v[196:199], v[36:39]
	v_mfma_f32_16x16x32_bf16 v[32:35], v[180:183], v[196:199], v[32:35]
	v_mfma_f32_16x16x32_bf16 v[20:23], v[172:175], v[204:207], v[20:23]
	v_mfma_f32_16x16x32_bf16 v[16:19], v[180:183], v[204:207], v[16:19]
	v_mfma_f32_16x16x32_bf16 v[4:7], v[172:175], v[228:231], v[4:7]
	v_mfma_f32_16x16x32_bf16 v[0:3], v[180:183], v[228:231], v[0:3]
	s_barrier
	s_add_i32 s13, s13, 0x80000
	s_mov_b32 m0, s82
	s_nop 0
	buffer_load_dwordx4 v220, s[64:67], s13 offen lds
	s_nop 0
	s_mov_b32 m0, s83
	s_nop 0
	buffer_load_dwordx4 v221, s[64:67], s13 offen lds
	v_add_u32_e32 v156, 0x18000, v222
	v_add_u32_e32 v180, 0x1c000, v222
	ds_read_b128 v[128:131], v156
	ds_read_b128 v[140:143], v156 offset:1024
	ds_read_b128 v[152:155], v156 offset:2048
	ds_read_b128 v[156:159], v156 offset:3072
	ds_read_b128 v[168:171], v180
	ds_read_b128 v[172:175], v180 offset:1024
	ds_read_b128 v[176:179], v180 offset:2048
	ds_read_b128 v[180:183], v180 offset:3072
	ds_read_b128 v[184:187], v223 offset:32768
	ds_read_b128 v[188:191], v223 offset:33792
	ds_read_b128 v[192:195], v223 offset:34816
	ds_read_b128 v[196:199], v223 offset:35840
	ds_read_b128 v[200:203], v223 offset:36864
	ds_read_b128 v[204:207], v223 offset:37888
	ds_read_b128 v[224:227], v223 offset:38912
	ds_read_b128 v[228:231], v223 offset:39936
	s_waitcnt vmcnt(8)
	s_waitcnt lgkmcnt(0)
	s_barrier
	s_waitcnt lgkmcnt(7)
	v_mfma_f32_16x16x32_bf16 v[164:167], v[128:131], v[184:187], v[164:167]
	v_mfma_f32_16x16x32_bf16 v[160:163], v[152:155], v[184:187], v[160:163]
	s_waitcnt lgkmcnt(5)
	v_mfma_f32_16x16x32_bf16 v[136:139], v[128:131], v[192:195], v[136:139]
	v_mfma_f32_16x16x32_bf16 v[132:135], v[152:155], v[192:195], v[132:135]
	s_waitcnt lgkmcnt(3)
	v_mfma_f32_16x16x32_bf16 v[116:119], v[128:131], v[200:203], v[116:119]
	v_mfma_f32_16x16x32_bf16 v[112:115], v[152:155], v[200:203], v[112:115]
	s_waitcnt lgkmcnt(1)
	v_mfma_f32_16x16x32_bf16 v[76:79], v[128:131], v[224:227], v[76:79]
	v_mfma_f32_16x16x32_bf16 v[72:75], v[152:155], v[224:227], v[72:75]
	v_mfma_f32_16x16x32_bf16 v[164:167], v[140:143], v[188:191], v[164:167]
	v_mfma_f32_16x16x32_bf16 v[160:163], v[156:159], v[188:191], v[160:163]
	v_mfma_f32_16x16x32_bf16 v[136:139], v[140:143], v[196:199], v[136:139]
	v_mfma_f32_16x16x32_bf16 v[132:135], v[156:159], v[196:199], v[132:135]
	v_mfma_f32_16x16x32_bf16 v[116:119], v[140:143], v[204:207], v[116:119]
	v_mfma_f32_16x16x32_bf16 v[112:115], v[156:159], v[204:207], v[112:115]
	s_waitcnt lgkmcnt(0)
	v_mfma_f32_16x16x32_bf16 v[76:79], v[140:143], v[228:231], v[76:79]
	v_mfma_f32_16x16x32_bf16 v[72:75], v[156:159], v[228:231], v[72:75]
	v_mfma_f32_16x16x32_bf16 v[148:151], v[168:171], v[184:187], v[148:151]
	v_mfma_f32_16x16x32_bf16 v[144:147], v[176:179], v[184:187], v[144:147]
	v_mfma_f32_16x16x32_bf16 v[124:127], v[168:171], v[192:195], v[124:127]
	v_mfma_f32_16x16x32_bf16 v[120:123], v[176:179], v[192:195], v[120:123]
	v_mfma_f32_16x16x32_bf16 v[108:111], v[168:171], v[200:203], v[108:111]
	v_mfma_f32_16x16x32_bf16 v[104:107], v[176:179], v[200:203], v[104:107]
	v_mfma_f32_16x16x32_bf16 v[68:71], v[168:171], v[224:227], v[68:71]
	v_mfma_f32_16x16x32_bf16 v[64:67], v[176:179], v[224:227], v[64:67]
	v_mfma_f32_16x16x32_bf16 v[148:151], v[172:175], v[188:191], v[148:151]
	v_mfma_f32_16x16x32_bf16 v[144:147], v[180:183], v[188:191], v[144:147]
	v_mfma_f32_16x16x32_bf16 v[124:127], v[172:175], v[196:199], v[124:127]
	v_mfma_f32_16x16x32_bf16 v[120:123], v[180:183], v[196:199], v[120:123]
	v_mfma_f32_16x16x32_bf16 v[108:111], v[172:175], v[204:207], v[108:111]
	v_mfma_f32_16x16x32_bf16 v[104:107], v[180:183], v[204:207], v[104:107]
	v_mfma_f32_16x16x32_bf16 v[68:71], v[172:175], v[228:231], v[68:71]
	v_mfma_f32_16x16x32_bf16 v[64:67], v[180:183], v[228:231], v[64:67]
	s_barrier
	s_or_b32 s13, s12, 0x4000
	s_mov_b32 m0, s34
	s_nop 0
	buffer_load_dwordx4 v220, s[48:51], s13 offen lds
	s_add_i32 s12, s12, 0x84000
	s_mov_b32 m0, s84
	s_nop 0
	buffer_load_dwordx4 v221, s[48:51], s13 offen lds
	s_nop 0
	s_mov_b32 m0, s87
	s_nop 0
	buffer_load_dwordx4 v220, s[48:51], s12 offen lds
	s_nop 0
	s_mov_b32 m0, s88
	s_nop 0
	buffer_load_dwordx4 v221, s[48:51], s12 offen lds
	s_nop 0
	s_mov_b32 m0, s85
	s_nop 0
	buffer_load_dwordx4 v220, s[64:67], s11 offen lds
	s_nop 0
	s_mov_b32 m0, s86
	s_nop 0
	buffer_load_dwordx4 v221, s[64:67], s11 offen lds
	ds_read_b128 v[184:187], v223 offset:49152
	ds_read_b128 v[188:191], v223 offset:50176
	ds_read_b128 v[192:195], v223 offset:51200
	ds_read_b128 v[196:199], v223 offset:52224
	ds_read_b128 v[200:203], v223 offset:53248
	ds_read_b128 v[204:207], v223 offset:54272
	ds_read_b128 v[224:227], v223 offset:55296
	ds_read_b128 v[228:231], v223 offset:56320
	s_waitcnt vmcnt(8)
	s_waitcnt lgkmcnt(0)
	s_barrier
	s_waitcnt lgkmcnt(7)
	v_mfma_f32_16x16x32_bf16 v[60:63], v[128:131], v[184:187], v[60:63]
	v_mfma_f32_16x16x32_bf16 v[56:59], v[152:155], v[184:187], v[56:59]
	s_waitcnt lgkmcnt(5)
	v_mfma_f32_16x16x32_bf16 v[44:47], v[128:131], v[192:195], v[44:47]
	v_mfma_f32_16x16x32_bf16 v[40:43], v[152:155], v[192:195], v[40:43]
	s_waitcnt lgkmcnt(3)
	v_mfma_f32_16x16x32_bf16 v[28:31], v[128:131], v[200:203], v[28:31]
	v_mfma_f32_16x16x32_bf16 v[24:27], v[152:155], v[200:203], v[24:27]
	s_waitcnt lgkmcnt(1)
	v_mfma_f32_16x16x32_bf16 v[12:15], v[128:131], v[224:227], v[12:15]
	v_mfma_f32_16x16x32_bf16 v[8:11], v[152:155], v[224:227], v[8:11]
	v_mfma_f32_16x16x32_bf16 v[60:63], v[140:143], v[188:191], v[60:63]
	v_mfma_f32_16x16x32_bf16 v[56:59], v[156:159], v[188:191], v[56:59]
	v_mfma_f32_16x16x32_bf16 v[44:47], v[140:143], v[196:199], v[44:47]
	v_mfma_f32_16x16x32_bf16 v[40:43], v[156:159], v[196:199], v[40:43]
	v_mfma_f32_16x16x32_bf16 v[28:31], v[140:143], v[204:207], v[28:31]
	v_mfma_f32_16x16x32_bf16 v[24:27], v[156:159], v[204:207], v[24:27]
	s_waitcnt lgkmcnt(0)
	v_mfma_f32_16x16x32_bf16 v[12:15], v[140:143], v[228:231], v[12:15]
	v_mfma_f32_16x16x32_bf16 v[8:11], v[156:159], v[228:231], v[8:11]
	v_mfma_f32_16x16x32_bf16 v[52:55], v[168:171], v[184:187], v[52:55]
	v_mfma_f32_16x16x32_bf16 v[48:51], v[176:179], v[184:187], v[48:51]
	v_mfma_f32_16x16x32_bf16 v[36:39], v[168:171], v[192:195], v[36:39]
	v_mfma_f32_16x16x32_bf16 v[32:35], v[176:179], v[192:195], v[32:35]
	v_mfma_f32_16x16x32_bf16 v[20:23], v[168:171], v[200:203], v[20:23]
	v_mfma_f32_16x16x32_bf16 v[16:19], v[176:179], v[200:203], v[16:19]
	v_mfma_f32_16x16x32_bf16 v[4:7], v[168:171], v[224:227], v[4:7]
	v_mfma_f32_16x16x32_bf16 v[0:3], v[176:179], v[224:227], v[0:3]
	v_mfma_f32_16x16x32_bf16 v[52:55], v[172:175], v[188:191], v[52:55]
	v_mfma_f32_16x16x32_bf16 v[48:51], v[180:183], v[188:191], v[48:51]
	v_mfma_f32_16x16x32_bf16 v[36:39], v[172:175], v[196:199], v[36:39]
	v_mfma_f32_16x16x32_bf16 v[32:35], v[180:183], v[196:199], v[32:35]
	v_mfma_f32_16x16x32_bf16 v[20:23], v[172:175], v[204:207], v[20:23]
	v_mfma_f32_16x16x32_bf16 v[16:19], v[180:183], v[204:207], v[16:19]
	v_mfma_f32_16x16x32_bf16 v[4:7], v[172:175], v[228:231], v[4:7]
	v_mfma_f32_16x16x32_bf16 v[0:3], v[180:183], v[228:231], v[0:3]
	s_barrier
	s_add_i32 s10, s10, 2
	s_add_i32 s8, s8, 0x8000
	s_add_i32 s9, s9, 0x8000
.LBB0_691:
	v_add_u32_e32 v156, 0x10000, v222
	v_add_u32_e32 v180, 0x14000, v222
	ds_read_b128 v[128:131], v156
	ds_read_b128 v[140:143], v156 offset:1024
	ds_read_b128 v[152:155], v156 offset:2048
	ds_read_b128 v[156:159], v156 offset:3072
	ds_read_b128 v[168:171], v180
	ds_read_b128 v[172:175], v180 offset:1024
	ds_read_b128 v[176:179], v180 offset:2048
	ds_read_b128 v[180:183], v180 offset:3072
	s_add_i32 s11, s8, 0xfff84000
	s_cmp_eq_u32 s10, 28
	s_cselect_b32 s13, s6, s11
	s_cselect_b32 s12, s7, s9
	s_or_b32 s11, s13, 0x4000
	ds_read_b128 v[184:187], v223
	ds_read_b128 v[188:191], v223 offset:1024
	ds_read_b128 v[192:195], v223 offset:2048
	ds_read_b128 v[196:199], v223 offset:3072
	ds_read_b128 v[200:203], v223 offset:4096
	ds_read_b128 v[204:207], v223 offset:5120
	ds_read_b128 v[224:227], v223 offset:6144
	ds_read_b128 v[228:231], v223 offset:7168
	s_mov_b32 m0, s89
	s_nop 0
	buffer_load_dwordx4 v220, s[64:67], s8 offen lds
	s_nop 0
	s_mov_b32 m0, s91
	s_nop 0
	buffer_load_dwordx4 v221, s[64:67], s8 offen lds
	s_waitcnt vmcnt(8)
	s_waitcnt lgkmcnt(0)
	s_barrier
	s_waitcnt lgkmcnt(7)
	v_mfma_f32_16x16x32_bf16 v[164:167], v[128:131], v[184:187], v[164:167]
	v_mfma_f32_16x16x32_bf16 v[160:163], v[152:155], v[184:187], v[160:163]
	s_waitcnt lgkmcnt(5)
	v_mfma_f32_16x16x32_bf16 v[136:139], v[128:131], v[192:195], v[136:139]
	v_mfma_f32_16x16x32_bf16 v[132:135], v[152:155], v[192:195], v[132:135]
	s_waitcnt lgkmcnt(3)
	v_mfma_f32_16x16x32_bf16 v[116:119], v[128:131], v[200:203], v[116:119]
	v_mfma_f32_16x16x32_bf16 v[112:115], v[152:155], v[200:203], v[112:115]
	s_waitcnt lgkmcnt(1)
	v_mfma_f32_16x16x32_bf16 v[76:79], v[128:131], v[224:227], v[76:79]
	v_mfma_f32_16x16x32_bf16 v[72:75], v[152:155], v[224:227], v[72:75]
	v_mfma_f32_16x16x32_bf16 v[164:167], v[140:143], v[188:191], v[164:167]
	v_mfma_f32_16x16x32_bf16 v[160:163], v[156:159], v[188:191], v[160:163]
	v_mfma_f32_16x16x32_bf16 v[136:139], v[140:143], v[196:199], v[136:139]
	v_mfma_f32_16x16x32_bf16 v[132:135], v[156:159], v[196:199], v[132:135]
	v_mfma_f32_16x16x32_bf16 v[116:119], v[140:143], v[204:207], v[116:119]
	v_mfma_f32_16x16x32_bf16 v[112:115], v[156:159], v[204:207], v[112:115]
	s_waitcnt lgkmcnt(0)
	v_mfma_f32_16x16x32_bf16 v[76:79], v[140:143], v[228:231], v[76:79]
	v_mfma_f32_16x16x32_bf16 v[72:75], v[156:159], v[228:231], v[72:75]
	v_mfma_f32_16x16x32_bf16 v[148:151], v[168:171], v[184:187], v[148:151]
	v_mfma_f32_16x16x32_bf16 v[144:147], v[176:179], v[184:187], v[144:147]
	v_mfma_f32_16x16x32_bf16 v[124:127], v[168:171], v[192:195], v[124:127]
	v_mfma_f32_16x16x32_bf16 v[120:123], v[176:179], v[192:195], v[120:123]
	v_mfma_f32_16x16x32_bf16 v[108:111], v[168:171], v[200:203], v[108:111]
	v_mfma_f32_16x16x32_bf16 v[104:107], v[176:179], v[200:203], v[104:107]
	v_mfma_f32_16x16x32_bf16 v[68:71], v[168:171], v[224:227], v[68:71]
	v_mfma_f32_16x16x32_bf16 v[64:67], v[176:179], v[224:227], v[64:67]
	v_mfma_f32_16x16x32_bf16 v[148:151], v[172:175], v[188:191], v[148:151]
	v_mfma_f32_16x16x32_bf16 v[144:147], v[180:183], v[188:191], v[144:147]
	v_mfma_f32_16x16x32_bf16 v[124:127], v[172:175], v[196:199], v[124:127]
	v_mfma_f32_16x16x32_bf16 v[120:123], v[180:183], v[196:199], v[120:123]
	v_mfma_f32_16x16x32_bf16 v[108:111], v[172:175], v[204:207], v[108:111]
	v_mfma_f32_16x16x32_bf16 v[104:107], v[180:183], v[204:207], v[104:107]
	v_mfma_f32_16x16x32_bf16 v[68:71], v[172:175], v[228:231], v[68:71]
	v_mfma_f32_16x16x32_bf16 v[64:67], v[180:183], v[228:231], v[64:67]
	s_barrier
	s_mov_b32 m0, s55
	s_nop 0
	buffer_load_dwordx4 v220, s[48:51], s12 offen lds
	s_add_i32 s14, s12, 0x80000
	s_mov_b32 m0, s76
	s_nop 0
	buffer_load_dwordx4 v221, s[48:51], s12 offen lds
	s_nop 0
	s_mov_b32 m0, s77
	s_nop 0
	buffer_load_dwordx4 v220, s[48:51], s14 offen lds
	s_nop 0
	s_mov_b32 m0, s78
	s_nop 0
	buffer_load_dwordx4 v221, s[48:51], s14 offen lds
	s_nop 0
	s_mov_b32 m0, s31
	s_nop 0
	buffer_load_dwordx4 v220, s[64:67], s13 offen lds
	s_nop 0
	s_mov_b32 m0, s79
	s_nop 0
	buffer_load_dwordx4 v221, s[64:67], s13 offen lds
	ds_read_b128 v[184:187], v223 offset:16384
	ds_read_b128 v[188:191], v223 offset:17408
	ds_read_b128 v[192:195], v223 offset:18432
	ds_read_b128 v[196:199], v223 offset:19456
	ds_read_b128 v[200:203], v223 offset:20480
	ds_read_b128 v[204:207], v223 offset:21504
	ds_read_b128 v[224:227], v223 offset:22528
	ds_read_b128 v[228:231], v223 offset:23552
	s_waitcnt vmcnt(8)
	s_waitcnt lgkmcnt(0)
	s_barrier
	s_waitcnt lgkmcnt(7)
	v_mfma_f32_16x16x32_bf16 v[60:63], v[128:131], v[184:187], v[60:63]
	v_mfma_f32_16x16x32_bf16 v[56:59], v[152:155], v[184:187], v[56:59]
	s_waitcnt lgkmcnt(5)
	v_mfma_f32_16x16x32_bf16 v[44:47], v[128:131], v[192:195], v[44:47]
	v_mfma_f32_16x16x32_bf16 v[40:43], v[152:155], v[192:195], v[40:43]
	s_waitcnt lgkmcnt(3)
	v_mfma_f32_16x16x32_bf16 v[28:31], v[128:131], v[200:203], v[28:31]
	v_mfma_f32_16x16x32_bf16 v[24:27], v[152:155], v[200:203], v[24:27]
	s_waitcnt lgkmcnt(1)
	v_mfma_f32_16x16x32_bf16 v[12:15], v[128:131], v[224:227], v[12:15]
	v_mfma_f32_16x16x32_bf16 v[8:11], v[152:155], v[224:227], v[8:11]
	v_mfma_f32_16x16x32_bf16 v[60:63], v[140:143], v[188:191], v[60:63]
	v_mfma_f32_16x16x32_bf16 v[56:59], v[156:159], v[188:191], v[56:59]
	v_mfma_f32_16x16x32_bf16 v[44:47], v[140:143], v[196:199], v[44:47]
	v_mfma_f32_16x16x32_bf16 v[40:43], v[156:159], v[196:199], v[40:43]
	v_mfma_f32_16x16x32_bf16 v[28:31], v[140:143], v[204:207], v[28:31]
	v_mfma_f32_16x16x32_bf16 v[24:27], v[156:159], v[204:207], v[24:27]
	s_waitcnt lgkmcnt(0)
	v_mfma_f32_16x16x32_bf16 v[12:15], v[140:143], v[228:231], v[12:15]
	v_mfma_f32_16x16x32_bf16 v[8:11], v[156:159], v[228:231], v[8:11]
	v_mfma_f32_16x16x32_bf16 v[52:55], v[168:171], v[184:187], v[52:55]
	v_mfma_f32_16x16x32_bf16 v[48:51], v[176:179], v[184:187], v[48:51]
	v_mfma_f32_16x16x32_bf16 v[36:39], v[168:171], v[192:195], v[36:39]
	v_mfma_f32_16x16x32_bf16 v[32:35], v[176:179], v[192:195], v[32:35]
	v_mfma_f32_16x16x32_bf16 v[20:23], v[168:171], v[200:203], v[20:23]
	v_mfma_f32_16x16x32_bf16 v[16:19], v[176:179], v[200:203], v[16:19]
	v_mfma_f32_16x16x32_bf16 v[4:7], v[168:171], v[224:227], v[4:7]
	v_mfma_f32_16x16x32_bf16 v[0:3], v[176:179], v[224:227], v[0:3]
	v_mfma_f32_16x16x32_bf16 v[52:55], v[172:175], v[188:191], v[52:55]
	v_mfma_f32_16x16x32_bf16 v[48:51], v[180:183], v[188:191], v[48:51]
	v_mfma_f32_16x16x32_bf16 v[36:39], v[172:175], v[196:199], v[36:39]
	v_mfma_f32_16x16x32_bf16 v[32:35], v[180:183], v[196:199], v[32:35]
	v_mfma_f32_16x16x32_bf16 v[20:23], v[172:175], v[204:207], v[20:23]
	v_mfma_f32_16x16x32_bf16 v[16:19], v[180:183], v[204:207], v[16:19]
	v_mfma_f32_16x16x32_bf16 v[4:7], v[172:175], v[228:231], v[4:7]
	v_mfma_f32_16x16x32_bf16 v[0:3], v[180:183], v[228:231], v[0:3]
	s_barrier
	s_add_i32 s13, s13, 0x80000
	s_mov_b32 m0, s82
	s_nop 0
	buffer_load_dwordx4 v220, s[64:67], s13 offen lds
	s_nop 0
	s_mov_b32 m0, s83
	s_nop 0
	buffer_load_dwordx4 v221, s[64:67], s13 offen lds
	v_add_u32_e32 v156, 0x18000, v222
	v_add_u32_e32 v180, 0x1c000, v222
	ds_read_b128 v[128:131], v156
	ds_read_b128 v[140:143], v156 offset:1024
	ds_read_b128 v[152:155], v156 offset:2048
	ds_read_b128 v[156:159], v156 offset:3072
	ds_read_b128 v[168:171], v180
	ds_read_b128 v[172:175], v180 offset:1024
	ds_read_b128 v[176:179], v180 offset:2048
	ds_read_b128 v[180:183], v180 offset:3072
	ds_read_b128 v[184:187], v223 offset:32768
	ds_read_b128 v[188:191], v223 offset:33792
	ds_read_b128 v[192:195], v223 offset:34816
	ds_read_b128 v[196:199], v223 offset:35840
	ds_read_b128 v[200:203], v223 offset:36864
	ds_read_b128 v[204:207], v223 offset:37888
	ds_read_b128 v[224:227], v223 offset:38912
	ds_read_b128 v[228:231], v223 offset:39936
	s_waitcnt vmcnt(8)
	s_waitcnt lgkmcnt(0)
	s_barrier
	s_waitcnt lgkmcnt(7)
	v_mfma_f32_16x16x32_bf16 v[164:167], v[128:131], v[184:187], v[164:167]
	v_mfma_f32_16x16x32_bf16 v[160:163], v[152:155], v[184:187], v[160:163]
	s_waitcnt lgkmcnt(5)
	v_mfma_f32_16x16x32_bf16 v[136:139], v[128:131], v[192:195], v[136:139]
	v_mfma_f32_16x16x32_bf16 v[132:135], v[152:155], v[192:195], v[132:135]
	s_waitcnt lgkmcnt(3)
	v_mfma_f32_16x16x32_bf16 v[116:119], v[128:131], v[200:203], v[116:119]
	v_mfma_f32_16x16x32_bf16 v[112:115], v[152:155], v[200:203], v[112:115]
	s_waitcnt lgkmcnt(1)
	v_mfma_f32_16x16x32_bf16 v[76:79], v[128:131], v[224:227], v[76:79]
	v_mfma_f32_16x16x32_bf16 v[72:75], v[152:155], v[224:227], v[72:75]
	v_mfma_f32_16x16x32_bf16 v[164:167], v[140:143], v[188:191], v[164:167]
	v_mfma_f32_16x16x32_bf16 v[160:163], v[156:159], v[188:191], v[160:163]
	v_mfma_f32_16x16x32_bf16 v[136:139], v[140:143], v[196:199], v[136:139]
	v_mfma_f32_16x16x32_bf16 v[132:135], v[156:159], v[196:199], v[132:135]
	v_mfma_f32_16x16x32_bf16 v[116:119], v[140:143], v[204:207], v[116:119]
	v_mfma_f32_16x16x32_bf16 v[112:115], v[156:159], v[204:207], v[112:115]
	s_waitcnt lgkmcnt(0)
	v_mfma_f32_16x16x32_bf16 v[76:79], v[140:143], v[228:231], v[76:79]
	v_mfma_f32_16x16x32_bf16 v[72:75], v[156:159], v[228:231], v[72:75]
	v_mfma_f32_16x16x32_bf16 v[148:151], v[168:171], v[184:187], v[148:151]
	v_mfma_f32_16x16x32_bf16 v[144:147], v[176:179], v[184:187], v[144:147]
	v_mfma_f32_16x16x32_bf16 v[124:127], v[168:171], v[192:195], v[124:127]
	v_mfma_f32_16x16x32_bf16 v[120:123], v[176:179], v[192:195], v[120:123]
	v_mfma_f32_16x16x32_bf16 v[108:111], v[168:171], v[200:203], v[108:111]
	v_mfma_f32_16x16x32_bf16 v[104:107], v[176:179], v[200:203], v[104:107]
	v_mfma_f32_16x16x32_bf16 v[68:71], v[168:171], v[224:227], v[68:71]
	v_mfma_f32_16x16x32_bf16 v[64:67], v[176:179], v[224:227], v[64:67]
	v_mfma_f32_16x16x32_bf16 v[148:151], v[172:175], v[188:191], v[148:151]
	v_mfma_f32_16x16x32_bf16 v[144:147], v[180:183], v[188:191], v[144:147]
	v_mfma_f32_16x16x32_bf16 v[124:127], v[172:175], v[196:199], v[124:127]
	v_mfma_f32_16x16x32_bf16 v[120:123], v[180:183], v[196:199], v[120:123]
	v_mfma_f32_16x16x32_bf16 v[108:111], v[172:175], v[204:207], v[108:111]
	v_mfma_f32_16x16x32_bf16 v[104:107], v[180:183], v[204:207], v[104:107]
	v_mfma_f32_16x16x32_bf16 v[68:71], v[172:175], v[228:231], v[68:71]
	v_mfma_f32_16x16x32_bf16 v[64:67], v[180:183], v[228:231], v[64:67]
	s_barrier
	s_or_b32 s13, s12, 0x4000
	s_mov_b32 m0, s34
	s_nop 0
	buffer_load_dwordx4 v220, s[48:51], s13 offen lds
	s_add_i32 s12, s12, 0x84000
	s_mov_b32 m0, s84
	s_nop 0
	buffer_load_dwordx4 v221, s[48:51], s13 offen lds
	s_nop 0
	s_mov_b32 m0, s87
	s_nop 0
	buffer_load_dwordx4 v220, s[48:51], s12 offen lds
	s_nop 0
	s_mov_b32 m0, s88
	s_nop 0
	buffer_load_dwordx4 v221, s[48:51], s12 offen lds
	s_nop 0
	s_mov_b32 m0, s85
	s_nop 0
	buffer_load_dwordx4 v220, s[64:67], s11 offen lds
	s_nop 0
	s_mov_b32 m0, s86
	s_nop 0
	buffer_load_dwordx4 v221, s[64:67], s11 offen lds
	ds_read_b128 v[184:187], v223 offset:49152
	ds_read_b128 v[188:191], v223 offset:50176
	ds_read_b128 v[192:195], v223 offset:51200
	ds_read_b128 v[196:199], v223 offset:52224
	ds_read_b128 v[200:203], v223 offset:53248
	ds_read_b128 v[204:207], v223 offset:54272
	ds_read_b128 v[224:227], v223 offset:55296
	ds_read_b128 v[228:231], v223 offset:56320
	s_waitcnt vmcnt(8)
	s_waitcnt lgkmcnt(0)
	s_barrier
	s_waitcnt lgkmcnt(7)
	v_mfma_f32_16x16x32_bf16 v[60:63], v[128:131], v[184:187], v[60:63]
	v_mfma_f32_16x16x32_bf16 v[56:59], v[152:155], v[184:187], v[56:59]
	s_waitcnt lgkmcnt(5)
	v_mfma_f32_16x16x32_bf16 v[44:47], v[128:131], v[192:195], v[44:47]
	v_mfma_f32_16x16x32_bf16 v[40:43], v[152:155], v[192:195], v[40:43]
	s_waitcnt lgkmcnt(3)
	v_mfma_f32_16x16x32_bf16 v[28:31], v[128:131], v[200:203], v[28:31]
	v_mfma_f32_16x16x32_bf16 v[24:27], v[152:155], v[200:203], v[24:27]
	s_waitcnt lgkmcnt(1)
	v_mfma_f32_16x16x32_bf16 v[12:15], v[128:131], v[224:227], v[12:15]
	v_mfma_f32_16x16x32_bf16 v[8:11], v[152:155], v[224:227], v[8:11]
	v_mfma_f32_16x16x32_bf16 v[60:63], v[140:143], v[188:191], v[60:63]
	v_mfma_f32_16x16x32_bf16 v[56:59], v[156:159], v[188:191], v[56:59]
	v_mfma_f32_16x16x32_bf16 v[44:47], v[140:143], v[196:199], v[44:47]
	v_mfma_f32_16x16x32_bf16 v[40:43], v[156:159], v[196:199], v[40:43]
	v_mfma_f32_16x16x32_bf16 v[28:31], v[140:143], v[204:207], v[28:31]
	v_mfma_f32_16x16x32_bf16 v[24:27], v[156:159], v[204:207], v[24:27]
	s_waitcnt lgkmcnt(0)
	v_mfma_f32_16x16x32_bf16 v[12:15], v[140:143], v[228:231], v[12:15]
	v_mfma_f32_16x16x32_bf16 v[8:11], v[156:159], v[228:231], v[8:11]
	v_mfma_f32_16x16x32_bf16 v[52:55], v[168:171], v[184:187], v[52:55]
	v_mfma_f32_16x16x32_bf16 v[48:51], v[176:179], v[184:187], v[48:51]
	v_mfma_f32_16x16x32_bf16 v[36:39], v[168:171], v[192:195], v[36:39]
	v_mfma_f32_16x16x32_bf16 v[32:35], v[176:179], v[192:195], v[32:35]
	v_mfma_f32_16x16x32_bf16 v[20:23], v[168:171], v[200:203], v[20:23]
	v_mfma_f32_16x16x32_bf16 v[16:19], v[176:179], v[200:203], v[16:19]
	v_mfma_f32_16x16x32_bf16 v[4:7], v[168:171], v[224:227], v[4:7]
	v_mfma_f32_16x16x32_bf16 v[0:3], v[176:179], v[224:227], v[0:3]
	v_mfma_f32_16x16x32_bf16 v[52:55], v[172:175], v[188:191], v[52:55]
	v_mfma_f32_16x16x32_bf16 v[48:51], v[180:183], v[188:191], v[48:51]
	v_mfma_f32_16x16x32_bf16 v[36:39], v[172:175], v[196:199], v[36:39]
	v_mfma_f32_16x16x32_bf16 v[32:35], v[180:183], v[196:199], v[32:35]
	v_mfma_f32_16x16x32_bf16 v[20:23], v[172:175], v[204:207], v[20:23]
	v_mfma_f32_16x16x32_bf16 v[16:19], v[180:183], v[204:207], v[16:19]
	v_mfma_f32_16x16x32_bf16 v[4:7], v[172:175], v[228:231], v[4:7]
	v_mfma_f32_16x16x32_bf16 v[0:3], v[180:183], v[228:231], v[0:3]
	s_barrier
	s_add_i32 s10, s10, 2
	s_add_i32 s8, s8, 0x8000
	s_add_i32 s9, s9, 0x8000
	s_cmp_gt_u32 s10, 29
	s_cbranch_scc0 .LBB0_691

.Lnb_p5:
	s_add_i32 s53, s37, 0xfff84000
	s_cmp_eq_u32 s52, 28
	s_cselect_b32 s56, s4, s53
	s_cselect_b32 s55, s5, s51
	s_or_b32 s53, s56, 0x4000
	s_mov_b32 m0, s41
	s_nop 0
	buffer_load_dwordx4 v166, s[24:27], s37 offen lds
	s_nop 0
	s_mov_b32 m0, s42
	s_nop 0
	buffer_load_dwordx4 v167, s[24:27], s37 offen lds
	s_waitcnt vmcnt(24)
	s_waitcnt lgkmcnt(0)
	s_barrier
	s_waitcnt lgkmcnt(7)
	v_mfma_f32_16x16x32_bf16 v[148:151], v[152:155], v[190:193], 0
	v_mfma_f32_16x16x32_bf16 v[140:143], v[160:163], v[190:193], 0
	s_waitcnt lgkmcnt(5)
	v_mfma_f32_16x16x32_bf16 v[132:135], v[152:155], v[198:201], 0
	v_mfma_f32_16x16x32_bf16 v[124:127], v[160:163], v[198:201], 0
	s_waitcnt lgkmcnt(3)
	v_mfma_f32_16x16x32_bf16 v[116:119], v[152:155], v[220:223], 0
	v_mfma_f32_16x16x32_bf16 v[108:111], v[160:163], v[220:223], 0
	s_waitcnt lgkmcnt(1)
	v_mfma_f32_16x16x32_bf16 v[76:79], v[152:155], v[228:231], 0
	v_mfma_f32_16x16x32_bf16 v[68:71], v[160:163], v[228:231], 0
	v_mfma_f32_16x16x32_bf16 v[148:151], v[156:159], v[194:197], v[148:151]
	v_mfma_f32_16x16x32_bf16 v[140:143], v[170:173], v[194:197], v[140:143]
	v_mfma_f32_16x16x32_bf16 v[132:135], v[156:159], v[202:205], v[132:135]
	v_mfma_f32_16x16x32_bf16 v[124:127], v[170:173], v[202:205], v[124:127]
	v_mfma_f32_16x16x32_bf16 v[116:119], v[156:159], v[224:227], v[116:119]
	v_mfma_f32_16x16x32_bf16 v[108:111], v[170:173], v[224:227], v[108:111]
	s_waitcnt lgkmcnt(0)
	v_mfma_f32_16x16x32_bf16 v[76:79], v[156:159], v[240:243], v[76:79]
	v_mfma_f32_16x16x32_bf16 v[68:71], v[170:173], v[240:243], v[68:71]
	v_mfma_f32_16x16x32_bf16 v[144:147], v[174:177], v[190:193], 0
	v_mfma_f32_16x16x32_bf16 v[136:139], v[182:185], v[190:193], 0
	v_mfma_f32_16x16x32_bf16 v[128:131], v[174:177], v[198:201], 0
	v_mfma_f32_16x16x32_bf16 v[120:123], v[182:185], v[198:201], 0
	v_mfma_f32_16x16x32_bf16 v[112:115], v[174:177], v[220:223], 0
	v_mfma_f32_16x16x32_bf16 v[104:107], v[182:185], v[220:223], 0
	v_mfma_f32_16x16x32_bf16 v[72:75], v[174:177], v[228:231], 0
	v_mfma_f32_16x16x32_bf16 v[64:67], v[182:185], v[228:231], 0
	v_mfma_f32_16x16x32_bf16 v[144:147], v[178:181], v[194:197], v[144:147]
	v_mfma_f32_16x16x32_bf16 v[136:139], v[186:189], v[194:197], v[136:139]
	v_mfma_f32_16x16x32_bf16 v[128:131], v[178:181], v[202:205], v[128:131]
	v_mfma_f32_16x16x32_bf16 v[120:123], v[186:189], v[202:205], v[120:123]
	v_mfma_f32_16x16x32_bf16 v[112:115], v[178:181], v[224:227], v[112:115]
	v_mfma_f32_16x16x32_bf16 v[104:107], v[186:189], v[224:227], v[104:107]
	v_mfma_f32_16x16x32_bf16 v[72:75], v[178:181], v[240:243], v[72:75]
	v_mfma_f32_16x16x32_bf16 v[64:67], v[186:189], v[240:243], v[64:67]
	s_barrier
	s_mov_b32 m0, s7
	s_nop 0
	buffer_load_dwordx4 v166, s[28:31], s55 offen lds
	s_add_i32 s57, s55, 0x80000
	s_mov_b32 m0, s8
	s_nop 0
	buffer_load_dwordx4 v167, s[28:31], s55 offen lds
	s_nop 0
	s_mov_b32 m0, s9
	s_nop 0
	buffer_load_dwordx4 v166, s[28:31], s57 offen lds
	s_nop 0
	s_mov_b32 m0, s10
	s_nop 0
	buffer_load_dwordx4 v167, s[28:31], s57 offen lds
	s_nop 0
	s_mov_b32 m0, s6
	s_nop 0
	buffer_load_dwordx4 v166, s[24:27], s56 offen lds
	s_nop 0
	s_mov_b32 m0, s11
	s_nop 0
	buffer_load_dwordx4 v167, s[24:27], s56 offen lds
	ds_read_b128 v[190:193], v169 offset:16384
	ds_read_b128 v[194:197], v169 offset:17408
	ds_read_b128 v[198:201], v169 offset:18432
	ds_read_b128 v[202:205], v169 offset:19456
	ds_read_b128 v[220:223], v169 offset:20480
	ds_read_b128 v[224:227], v169 offset:21504
	ds_read_b128 v[228:231], v169 offset:22528
	ds_read_b128 v[240:243], v169 offset:23552
	s_waitcnt vmcnt(24)
	s_waitcnt lgkmcnt(0)
	s_barrier
	s_waitcnt lgkmcnt(7)
	v_mfma_f32_16x16x32_bf16 v[60:63], v[152:155], v[190:193], 0
	v_mfma_f32_16x16x32_bf16 v[52:55], v[160:163], v[190:193], 0
	s_waitcnt lgkmcnt(5)
	v_mfma_f32_16x16x32_bf16 v[44:47], v[152:155], v[198:201], 0
	v_mfma_f32_16x16x32_bf16 v[36:39], v[160:163], v[198:201], 0
	s_waitcnt lgkmcnt(3)
	v_mfma_f32_16x16x32_bf16 v[28:31], v[152:155], v[220:223], 0
	v_mfma_f32_16x16x32_bf16 v[20:23], v[160:163], v[220:223], 0
	s_waitcnt lgkmcnt(1)
	v_mfma_f32_16x16x32_bf16 v[12:15], v[152:155], v[228:231], 0
	v_mfma_f32_16x16x32_bf16 v[4:7], v[160:163], v[228:231], 0
	v_mfma_f32_16x16x32_bf16 v[60:63], v[156:159], v[194:197], v[60:63]
	v_mfma_f32_16x16x32_bf16 v[52:55], v[170:173], v[194:197], v[52:55]
	v_mfma_f32_16x16x32_bf16 v[44:47], v[156:159], v[202:205], v[44:47]
	v_mfma_f32_16x16x32_bf16 v[36:39], v[170:173], v[202:205], v[36:39]
	v_mfma_f32_16x16x32_bf16 v[28:31], v[156:159], v[224:227], v[28:31]
	v_mfma_f32_16x16x32_bf16 v[20:23], v[170:173], v[224:227], v[20:23]
	s_waitcnt lgkmcnt(0)
	v_mfma_f32_16x16x32_bf16 v[12:15], v[156:159], v[240:243], v[12:15]
	v_mfma_f32_16x16x32_bf16 v[4:7], v[170:173], v[240:243], v[4:7]
	v_mfma_f32_16x16x32_bf16 v[56:59], v[174:177], v[190:193], 0
	v_mfma_f32_16x16x32_bf16 v[48:51], v[182:185], v[190:193], 0
	v_mfma_f32_16x16x32_bf16 v[40:43], v[174:177], v[198:201], 0
	v_mfma_f32_16x16x32_bf16 v[32:35], v[182:185], v[198:201], 0
	v_mfma_f32_16x16x32_bf16 v[24:27], v[174:177], v[220:223], 0
	v_mfma_f32_16x16x32_bf16 v[16:19], v[182:185], v[220:223], 0
	v_mfma_f32_16x16x32_bf16 v[8:11], v[174:177], v[228:231], 0
	v_mfma_f32_16x16x32_bf16 v[0:3], v[182:185], v[228:231], 0
	v_mfma_f32_16x16x32_bf16 v[56:59], v[178:181], v[194:197], v[56:59]
	v_mfma_f32_16x16x32_bf16 v[48:51], v[186:189], v[194:197], v[48:51]
	v_mfma_f32_16x16x32_bf16 v[40:43], v[178:181], v[202:205], v[40:43]
	v_mfma_f32_16x16x32_bf16 v[32:35], v[186:189], v[202:205], v[32:35]
	v_mfma_f32_16x16x32_bf16 v[24:27], v[178:181], v[224:227], v[24:27]
	v_mfma_f32_16x16x32_bf16 v[16:19], v[186:189], v[224:227], v[16:19]
	v_mfma_f32_16x16x32_bf16 v[8:11], v[178:181], v[240:243], v[8:11]
	v_mfma_f32_16x16x32_bf16 v[0:3], v[186:189], v[240:243], v[0:3]
	s_barrier
	s_add_i32 s56, s56, 0x80000
	s_mov_b32 m0, s12
	s_nop 0
	buffer_load_dwordx4 v166, s[24:27], s56 offen lds
	s_nop 0
	s_mov_b32 m0, s13
	s_nop 0
	buffer_load_dwordx4 v167, s[24:27], s56 offen lds
	v_add_u32_e32 v164, 0x18000, v168
	ds_read_b128 v[152:155], v164
	ds_read_b128 v[156:159], v164 offset:1024
	ds_read_b128 v[160:163], v164 offset:2048
	ds_read_b128 v[170:173], v164 offset:3072
	v_add_u32_e32 v164, 0x1c000, v168
	ds_read_b128 v[174:177], v164
	ds_read_b128 v[178:181], v164 offset:1024
	ds_read_b128 v[182:185], v164 offset:2048
	ds_read_b128 v[186:189], v164 offset:3072
	ds_read_b128 v[190:193], v169 offset:32768
	ds_read_b128 v[194:197], v169 offset:33792
	ds_read_b128 v[198:201], v169 offset:34816
	ds_read_b128 v[202:205], v169 offset:35840
	ds_read_b128 v[220:223], v169 offset:36864
	ds_read_b128 v[224:227], v169 offset:37888
	ds_read_b128 v[228:231], v169 offset:38912
	ds_read_b128 v[240:243], v169 offset:39936
	s_waitcnt vmcnt(8)
	s_waitcnt lgkmcnt(0)
	s_barrier
	s_waitcnt lgkmcnt(7)
	v_mfma_f32_16x16x32_bf16 v[148:151], v[152:155], v[190:193], v[148:151]
	v_mfma_f32_16x16x32_bf16 v[140:143], v[160:163], v[190:193], v[140:143]
	s_waitcnt lgkmcnt(5)
	v_mfma_f32_16x16x32_bf16 v[132:135], v[152:155], v[198:201], v[132:135]
	v_mfma_f32_16x16x32_bf16 v[124:127], v[160:163], v[198:201], v[124:127]
	s_waitcnt lgkmcnt(3)
	v_mfma_f32_16x16x32_bf16 v[116:119], v[152:155], v[220:223], v[116:119]
	v_mfma_f32_16x16x32_bf16 v[108:111], v[160:163], v[220:223], v[108:111]
	s_waitcnt lgkmcnt(1)
	v_mfma_f32_16x16x32_bf16 v[76:79], v[152:155], v[228:231], v[76:79]
	v_mfma_f32_16x16x32_bf16 v[68:71], v[160:163], v[228:231], v[68:71]
	v_mfma_f32_16x16x32_bf16 v[148:151], v[156:159], v[194:197], v[148:151]
	v_mfma_f32_16x16x32_bf16 v[140:143], v[170:173], v[194:197], v[140:143]
	v_mfma_f32_16x16x32_bf16 v[132:135], v[156:159], v[202:205], v[132:135]
	v_mfma_f32_16x16x32_bf16 v[124:127], v[170:173], v[202:205], v[124:127]
	v_mfma_f32_16x16x32_bf16 v[116:119], v[156:159], v[224:227], v[116:119]
	v_mfma_f32_16x16x32_bf16 v[108:111], v[170:173], v[224:227], v[108:111]
	s_waitcnt lgkmcnt(0)
	v_mfma_f32_16x16x32_bf16 v[76:79], v[156:159], v[240:243], v[76:79]
	v_mfma_f32_16x16x32_bf16 v[68:71], v[170:173], v[240:243], v[68:71]
	v_mfma_f32_16x16x32_bf16 v[144:147], v[174:177], v[190:193], v[144:147]
	v_mfma_f32_16x16x32_bf16 v[136:139], v[182:185], v[190:193], v[136:139]
	v_mfma_f32_16x16x32_bf16 v[128:131], v[174:177], v[198:201], v[128:131]
	v_mfma_f32_16x16x32_bf16 v[120:123], v[182:185], v[198:201], v[120:123]
	v_mfma_f32_16x16x32_bf16 v[112:115], v[174:177], v[220:223], v[112:115]
	v_mfma_f32_16x16x32_bf16 v[104:107], v[182:185], v[220:223], v[104:107]
	v_mfma_f32_16x16x32_bf16 v[72:75], v[174:177], v[228:231], v[72:75]
	v_mfma_f32_16x16x32_bf16 v[64:67], v[182:185], v[228:231], v[64:67]
	v_mfma_f32_16x16x32_bf16 v[144:147], v[178:181], v[194:197], v[144:147]
	v_mfma_f32_16x16x32_bf16 v[136:139], v[186:189], v[194:197], v[136:139]
	v_mfma_f32_16x16x32_bf16 v[128:131], v[178:181], v[202:205], v[128:131]
	v_mfma_f32_16x16x32_bf16 v[120:123], v[186:189], v[202:205], v[120:123]
	v_mfma_f32_16x16x32_bf16 v[112:115], v[178:181], v[224:227], v[112:115]
	v_mfma_f32_16x16x32_bf16 v[104:107], v[186:189], v[224:227], v[104:107]
	v_mfma_f32_16x16x32_bf16 v[72:75], v[178:181], v[240:243], v[72:75]
	v_mfma_f32_16x16x32_bf16 v[64:67], v[186:189], v[240:243], v[64:67]
	s_barrier
	s_or_b32 s56, s55, 0x4000
	s_mov_b32 m0, s16
	s_nop 0
	buffer_load_dwordx4 v166, s[28:31], s56 offen lds
	s_add_i32 s55, s55, 0x84000
	s_mov_b32 m0, s17
	s_nop 0
	buffer_load_dwordx4 v167, s[28:31], s56 offen lds
	s_nop 0
	s_mov_b32 m0, s34
	s_nop 0
	buffer_load_dwordx4 v166, s[28:31], s55 offen lds
	s_nop 0
	s_mov_b32 m0, s40
	s_nop 0
	buffer_load_dwordx4 v167, s[28:31], s55 offen lds
	s_nop 0
	s_mov_b32 m0, s18
	s_nop 0
	buffer_load_dwordx4 v166, s[24:27], s53 offen lds
	s_nop 0
	s_mov_b32 m0, s19
	s_nop 0
	buffer_load_dwordx4 v167, s[24:27], s53 offen lds
	ds_read_b128 v[190:193], v169 offset:49152
	ds_read_b128 v[194:197], v169 offset:50176
	ds_read_b128 v[198:201], v169 offset:51200
	ds_read_b128 v[202:205], v169 offset:52224
	ds_read_b128 v[220:223], v169 offset:53248
	ds_read_b128 v[224:227], v169 offset:54272
	ds_read_b128 v[228:231], v169 offset:55296
	ds_read_b128 v[240:243], v169 offset:56320
	s_waitcnt vmcnt(8)
	s_waitcnt lgkmcnt(0)
	s_barrier
	s_waitcnt lgkmcnt(7)
	v_mfma_f32_16x16x32_bf16 v[60:63], v[152:155], v[190:193], v[60:63]
	v_mfma_f32_16x16x32_bf16 v[52:55], v[160:163], v[190:193], v[52:55]
	s_waitcnt lgkmcnt(5)
	v_mfma_f32_16x16x32_bf16 v[44:47], v[152:155], v[198:201], v[44:47]
	v_mfma_f32_16x16x32_bf16 v[36:39], v[160:163], v[198:201], v[36:39]
	s_waitcnt lgkmcnt(3)
	v_mfma_f32_16x16x32_bf16 v[28:31], v[152:155], v[220:223], v[28:31]
	v_mfma_f32_16x16x32_bf16 v[20:23], v[160:163], v[220:223], v[20:23]
	s_waitcnt lgkmcnt(1)
	v_mfma_f32_16x16x32_bf16 v[12:15], v[152:155], v[228:231], v[12:15]
	v_mfma_f32_16x16x32_bf16 v[4:7], v[160:163], v[228:231], v[4:7]
	v_mfma_f32_16x16x32_bf16 v[60:63], v[156:159], v[194:197], v[60:63]
	v_mfma_f32_16x16x32_bf16 v[52:55], v[170:173], v[194:197], v[52:55]
	v_mfma_f32_16x16x32_bf16 v[44:47], v[156:159], v[202:205], v[44:47]
	v_mfma_f32_16x16x32_bf16 v[36:39], v[170:173], v[202:205], v[36:39]
	v_mfma_f32_16x16x32_bf16 v[28:31], v[156:159], v[224:227], v[28:31]
	v_mfma_f32_16x16x32_bf16 v[20:23], v[170:173], v[224:227], v[20:23]
	s_waitcnt lgkmcnt(0)
	v_mfma_f32_16x16x32_bf16 v[12:15], v[156:159], v[240:243], v[12:15]
	v_mfma_f32_16x16x32_bf16 v[4:7], v[170:173], v[240:243], v[4:7]
	v_mfma_f32_16x16x32_bf16 v[56:59], v[174:177], v[190:193], v[56:59]
	v_mfma_f32_16x16x32_bf16 v[48:51], v[182:185], v[190:193], v[48:51]
	v_mfma_f32_16x16x32_bf16 v[40:43], v[174:177], v[198:201], v[40:43]
	v_mfma_f32_16x16x32_bf16 v[32:35], v[182:185], v[198:201], v[32:35]
	v_mfma_f32_16x16x32_bf16 v[24:27], v[174:177], v[220:223], v[24:27]
	v_mfma_f32_16x16x32_bf16 v[16:19], v[182:185], v[220:223], v[16:19]
	v_mfma_f32_16x16x32_bf16 v[8:11], v[174:177], v[228:231], v[8:11]
	v_mfma_f32_16x16x32_bf16 v[0:3], v[182:185], v[228:231], v[0:3]
	v_mfma_f32_16x16x32_bf16 v[56:59], v[178:181], v[194:197], v[56:59]
	v_mfma_f32_16x16x32_bf16 v[48:51], v[186:189], v[194:197], v[48:51]
	v_mfma_f32_16x16x32_bf16 v[40:43], v[178:181], v[202:205], v[40:43]
	v_mfma_f32_16x16x32_bf16 v[32:35], v[186:189], v[202:205], v[32:35]
	v_mfma_f32_16x16x32_bf16 v[24:27], v[178:181], v[224:227], v[24:27]
	v_mfma_f32_16x16x32_bf16 v[16:19], v[186:189], v[224:227], v[16:19]
	v_mfma_f32_16x16x32_bf16 v[8:11], v[178:181], v[240:243], v[8:11]
	v_mfma_f32_16x16x32_bf16 v[0:3], v[186:189], v[240:243], v[0:3]
	s_barrier
	s_add_i32 s52, s52, 2
	s_add_i32 s37, s37, 0x8000
	s_add_i32 s51, s51, 0x8000
.LBB0_795:
	v_add_u32_e32 v164, 0x10000, v168
	ds_read_b128 v[152:155], v164
	ds_read_b128 v[156:159], v164 offset:1024
	ds_read_b128 v[160:163], v164 offset:2048
	ds_read_b128 v[170:173], v164 offset:3072
	v_add_u32_e32 v164, 0x14000, v168
	ds_read_b128 v[174:177], v164
	ds_read_b128 v[178:181], v164 offset:1024
	ds_read_b128 v[182:185], v164 offset:2048
	ds_read_b128 v[186:189], v164 offset:3072
	s_add_i32 s53, s37, 0xfff84000
	s_cmp_eq_u32 s52, 28
	s_cselect_b32 s56, s4, s53
	s_cselect_b32 s55, s5, s51
	s_or_b32 s53, s56, 0x4000
	ds_read_b128 v[190:193], v169
	ds_read_b128 v[194:197], v169 offset:1024
	ds_read_b128 v[198:201], v169 offset:2048
	ds_read_b128 v[202:205], v169 offset:3072
	ds_read_b128 v[220:223], v169 offset:4096
	ds_read_b128 v[224:227], v169 offset:5120
	ds_read_b128 v[228:231], v169 offset:6144
	ds_read_b128 v[240:243], v169 offset:7168
	s_mov_b32 m0, s41
	s_nop 0
	buffer_load_dwordx4 v166, s[24:27], s37 offen lds
	s_nop 0
	s_mov_b32 m0, s42
	s_nop 0
	buffer_load_dwordx4 v167, s[24:27], s37 offen lds
	s_waitcnt vmcnt(8)
	s_waitcnt lgkmcnt(0)
	s_barrier
	s_waitcnt lgkmcnt(7)
	v_mfma_f32_16x16x32_bf16 v[148:151], v[152:155], v[190:193], v[148:151]
	v_mfma_f32_16x16x32_bf16 v[140:143], v[160:163], v[190:193], v[140:143]
	s_waitcnt lgkmcnt(5)
	v_mfma_f32_16x16x32_bf16 v[132:135], v[152:155], v[198:201], v[132:135]
	v_mfma_f32_16x16x32_bf16 v[124:127], v[160:163], v[198:201], v[124:127]
	s_waitcnt lgkmcnt(3)
	v_mfma_f32_16x16x32_bf16 v[116:119], v[152:155], v[220:223], v[116:119]
	v_mfma_f32_16x16x32_bf16 v[108:111], v[160:163], v[220:223], v[108:111]
	s_waitcnt lgkmcnt(1)
	v_mfma_f32_16x16x32_bf16 v[76:79], v[152:155], v[228:231], v[76:79]
	v_mfma_f32_16x16x32_bf16 v[68:71], v[160:163], v[228:231], v[68:71]
	v_mfma_f32_16x16x32_bf16 v[148:151], v[156:159], v[194:197], v[148:151]
	v_mfma_f32_16x16x32_bf16 v[140:143], v[170:173], v[194:197], v[140:143]
	v_mfma_f32_16x16x32_bf16 v[132:135], v[156:159], v[202:205], v[132:135]
	v_mfma_f32_16x16x32_bf16 v[124:127], v[170:173], v[202:205], v[124:127]
	v_mfma_f32_16x16x32_bf16 v[116:119], v[156:159], v[224:227], v[116:119]
	v_mfma_f32_16x16x32_bf16 v[108:111], v[170:173], v[224:227], v[108:111]
	s_waitcnt lgkmcnt(0)
	v_mfma_f32_16x16x32_bf16 v[76:79], v[156:159], v[240:243], v[76:79]
	v_mfma_f32_16x16x32_bf16 v[68:71], v[170:173], v[240:243], v[68:71]
	v_mfma_f32_16x16x32_bf16 v[144:147], v[174:177], v[190:193], v[144:147]
	v_mfma_f32_16x16x32_bf16 v[136:139], v[182:185], v[190:193], v[136:139]
	v_mfma_f32_16x16x32_bf16 v[128:131], v[174:177], v[198:201], v[128:131]
	v_mfma_f32_16x16x32_bf16 v[120:123], v[182:185], v[198:201], v[120:123]
	v_mfma_f32_16x16x32_bf16 v[112:115], v[174:177], v[220:223], v[112:115]
	v_mfma_f32_16x16x32_bf16 v[104:107], v[182:185], v[220:223], v[104:107]
	v_mfma_f32_16x16x32_bf16 v[72:75], v[174:177], v[228:231], v[72:75]
	v_mfma_f32_16x16x32_bf16 v[64:67], v[182:185], v[228:231], v[64:67]
	v_mfma_f32_16x16x32_bf16 v[144:147], v[178:181], v[194:197], v[144:147]
	v_mfma_f32_16x16x32_bf16 v[136:139], v[186:189], v[194:197], v[136:139]
	v_mfma_f32_16x16x32_bf16 v[128:131], v[178:181], v[202:205], v[128:131]
	v_mfma_f32_16x16x32_bf16 v[120:123], v[186:189], v[202:205], v[120:123]
	v_mfma_f32_16x16x32_bf16 v[112:115], v[178:181], v[224:227], v[112:115]
	v_mfma_f32_16x16x32_bf16 v[104:107], v[186:189], v[224:227], v[104:107]
	v_mfma_f32_16x16x32_bf16 v[72:75], v[178:181], v[240:243], v[72:75]
	v_mfma_f32_16x16x32_bf16 v[64:67], v[186:189], v[240:243], v[64:67]
	s_barrier
	s_mov_b32 m0, s7
	s_nop 0
	buffer_load_dwordx4 v166, s[28:31], s55 offen lds
	s_add_i32 s57, s55, 0x80000
	s_mov_b32 m0, s8
	s_nop 0
	buffer_load_dwordx4 v167, s[28:31], s55 offen lds
	s_nop 0
	s_mov_b32 m0, s9
	s_nop 0
	buffer_load_dwordx4 v166, s[28:31], s57 offen lds
	s_nop 0
	s_mov_b32 m0, s10
	s_nop 0
	buffer_load_dwordx4 v167, s[28:31], s57 offen lds
	s_nop 0
	s_mov_b32 m0, s6
	s_nop 0
	buffer_load_dwordx4 v166, s[24:27], s56 offen lds
	s_nop 0
	s_mov_b32 m0, s11
	s_nop 0
	buffer_load_dwordx4 v167, s[24:27], s56 offen lds
	ds_read_b128 v[190:193], v169 offset:16384
	ds_read_b128 v[194:197], v169 offset:17408
	ds_read_b128 v[198:201], v169 offset:18432
	ds_read_b128 v[202:205], v169 offset:19456
	ds_read_b128 v[220:223], v169 offset:20480
	ds_read_b128 v[224:227], v169 offset:21504
	ds_read_b128 v[228:231], v169 offset:22528
	ds_read_b128 v[240:243], v169 offset:23552
	s_waitcnt vmcnt(8)
	s_waitcnt lgkmcnt(0)
	s_barrier
	s_waitcnt lgkmcnt(7)
	v_mfma_f32_16x16x32_bf16 v[60:63], v[152:155], v[190:193], v[60:63]
	v_mfma_f32_16x16x32_bf16 v[52:55], v[160:163], v[190:193], v[52:55]
	s_waitcnt lgkmcnt(5)
	v_mfma_f32_16x16x32_bf16 v[44:47], v[152:155], v[198:201], v[44:47]
	v_mfma_f32_16x16x32_bf16 v[36:39], v[160:163], v[198:201], v[36:39]
	s_waitcnt lgkmcnt(3)
	v_mfma_f32_16x16x32_bf16 v[28:31], v[152:155], v[220:223], v[28:31]
	v_mfma_f32_16x16x32_bf16 v[20:23], v[160:163], v[220:223], v[20:23]
	s_waitcnt lgkmcnt(1)
	v_mfma_f32_16x16x32_bf16 v[12:15], v[152:155], v[228:231], v[12:15]
	v_mfma_f32_16x16x32_bf16 v[4:7], v[160:163], v[228:231], v[4:7]
	v_mfma_f32_16x16x32_bf16 v[60:63], v[156:159], v[194:197], v[60:63]
	v_mfma_f32_16x16x32_bf16 v[52:55], v[170:173], v[194:197], v[52:55]
	v_mfma_f32_16x16x32_bf16 v[44:47], v[156:159], v[202:205], v[44:47]
	v_mfma_f32_16x16x32_bf16 v[36:39], v[170:173], v[202:205], v[36:39]
	v_mfma_f32_16x16x32_bf16 v[28:31], v[156:159], v[224:227], v[28:31]
	v_mfma_f32_16x16x32_bf16 v[20:23], v[170:173], v[224:227], v[20:23]
	s_waitcnt lgkmcnt(0)
	v_mfma_f32_16x16x32_bf16 v[12:15], v[156:159], v[240:243], v[12:15]
	v_mfma_f32_16x16x32_bf16 v[4:7], v[170:173], v[240:243], v[4:7]
	v_mfma_f32_16x16x32_bf16 v[56:59], v[174:177], v[190:193], v[56:59]
	v_mfma_f32_16x16x32_bf16 v[48:51], v[182:185], v[190:193], v[48:51]
	v_mfma_f32_16x16x32_bf16 v[40:43], v[174:177], v[198:201], v[40:43]
	v_mfma_f32_16x16x32_bf16 v[32:35], v[182:185], v[198:201], v[32:35]
	v_mfma_f32_16x16x32_bf16 v[24:27], v[174:177], v[220:223], v[24:27]
	v_mfma_f32_16x16x32_bf16 v[16:19], v[182:185], v[220:223], v[16:19]
	v_mfma_f32_16x16x32_bf16 v[8:11], v[174:177], v[228:231], v[8:11]
	v_mfma_f32_16x16x32_bf16 v[0:3], v[182:185], v[228:231], v[0:3]
	v_mfma_f32_16x16x32_bf16 v[56:59], v[178:181], v[194:197], v[56:59]
	v_mfma_f32_16x16x32_bf16 v[48:51], v[186:189], v[194:197], v[48:51]
	v_mfma_f32_16x16x32_bf16 v[40:43], v[178:181], v[202:205], v[40:43]
	v_mfma_f32_16x16x32_bf16 v[32:35], v[186:189], v[202:205], v[32:35]
	v_mfma_f32_16x16x32_bf16 v[24:27], v[178:181], v[224:227], v[24:27]
	v_mfma_f32_16x16x32_bf16 v[16:19], v[186:189], v[224:227], v[16:19]
	v_mfma_f32_16x16x32_bf16 v[8:11], v[178:181], v[240:243], v[8:11]
	v_mfma_f32_16x16x32_bf16 v[0:3], v[186:189], v[240:243], v[0:3]
	s_barrier
	s_add_i32 s56, s56, 0x80000
	s_mov_b32 m0, s12
	s_nop 0
	buffer_load_dwordx4 v166, s[24:27], s56 offen lds
	s_nop 0
	s_mov_b32 m0, s13
	s_nop 0
	buffer_load_dwordx4 v167, s[24:27], s56 offen lds
	v_add_u32_e32 v164, 0x18000, v168
	ds_read_b128 v[152:155], v164
	ds_read_b128 v[156:159], v164 offset:1024
	ds_read_b128 v[160:163], v164 offset:2048
	ds_read_b128 v[170:173], v164 offset:3072
	v_add_u32_e32 v164, 0x1c000, v168
	ds_read_b128 v[174:177], v164
	ds_read_b128 v[178:181], v164 offset:1024
	ds_read_b128 v[182:185], v164 offset:2048
	ds_read_b128 v[186:189], v164 offset:3072
	ds_read_b128 v[190:193], v169 offset:32768
	ds_read_b128 v[194:197], v169 offset:33792
	ds_read_b128 v[198:201], v169 offset:34816
	ds_read_b128 v[202:205], v169 offset:35840
	ds_read_b128 v[220:223], v169 offset:36864
	ds_read_b128 v[224:227], v169 offset:37888
	ds_read_b128 v[228:231], v169 offset:38912
	ds_read_b128 v[240:243], v169 offset:39936
	s_waitcnt vmcnt(8)
	s_waitcnt lgkmcnt(0)
	s_barrier
	s_waitcnt lgkmcnt(7)
	v_mfma_f32_16x16x32_bf16 v[148:151], v[152:155], v[190:193], v[148:151]
	v_mfma_f32_16x16x32_bf16 v[140:143], v[160:163], v[190:193], v[140:143]
	s_waitcnt lgkmcnt(5)
	v_mfma_f32_16x16x32_bf16 v[132:135], v[152:155], v[198:201], v[132:135]
	v_mfma_f32_16x16x32_bf16 v[124:127], v[160:163], v[198:201], v[124:127]
	s_waitcnt lgkmcnt(3)
	v_mfma_f32_16x16x32_bf16 v[116:119], v[152:155], v[220:223], v[116:119]
	v_mfma_f32_16x16x32_bf16 v[108:111], v[160:163], v[220:223], v[108:111]
	s_waitcnt lgkmcnt(1)
	v_mfma_f32_16x16x32_bf16 v[76:79], v[152:155], v[228:231], v[76:79]
	v_mfma_f32_16x16x32_bf16 v[68:71], v[160:163], v[228:231], v[68:71]
	v_mfma_f32_16x16x32_bf16 v[148:151], v[156:159], v[194:197], v[148:151]
	v_mfma_f32_16x16x32_bf16 v[140:143], v[170:173], v[194:197], v[140:143]
	v_mfma_f32_16x16x32_bf16 v[132:135], v[156:159], v[202:205], v[132:135]
	v_mfma_f32_16x16x32_bf16 v[124:127], v[170:173], v[202:205], v[124:127]
	v_mfma_f32_16x16x32_bf16 v[116:119], v[156:159], v[224:227], v[116:119]
	v_mfma_f32_16x16x32_bf16 v[108:111], v[170:173], v[224:227], v[108:111]
	s_waitcnt lgkmcnt(0)
	v_mfma_f32_16x16x32_bf16 v[76:79], v[156:159], v[240:243], v[76:79]
	v_mfma_f32_16x16x32_bf16 v[68:71], v[170:173], v[240:243], v[68:71]
	v_mfma_f32_16x16x32_bf16 v[144:147], v[174:177], v[190:193], v[144:147]
	v_mfma_f32_16x16x32_bf16 v[136:139], v[182:185], v[190:193], v[136:139]
	v_mfma_f32_16x16x32_bf16 v[128:131], v[174:177], v[198:201], v[128:131]
	v_mfma_f32_16x16x32_bf16 v[120:123], v[182:185], v[198:201], v[120:123]
	v_mfma_f32_16x16x32_bf16 v[112:115], v[174:177], v[220:223], v[112:115]
	v_mfma_f32_16x16x32_bf16 v[104:107], v[182:185], v[220:223], v[104:107]
	v_mfma_f32_16x16x32_bf16 v[72:75], v[174:177], v[228:231], v[72:75]
	v_mfma_f32_16x16x32_bf16 v[64:67], v[182:185], v[228:231], v[64:67]
	v_mfma_f32_16x16x32_bf16 v[144:147], v[178:181], v[194:197], v[144:147]
	v_mfma_f32_16x16x32_bf16 v[136:139], v[186:189], v[194:197], v[136:139]
	v_mfma_f32_16x16x32_bf16 v[128:131], v[178:181], v[202:205], v[128:131]
	v_mfma_f32_16x16x32_bf16 v[120:123], v[186:189], v[202:205], v[120:123]
	v_mfma_f32_16x16x32_bf16 v[112:115], v[178:181], v[224:227], v[112:115]
	v_mfma_f32_16x16x32_bf16 v[104:107], v[186:189], v[224:227], v[104:107]
	v_mfma_f32_16x16x32_bf16 v[72:75], v[178:181], v[240:243], v[72:75]
	v_mfma_f32_16x16x32_bf16 v[64:67], v[186:189], v[240:243], v[64:67]
	s_barrier
	s_or_b32 s56, s55, 0x4000
	s_mov_b32 m0, s16
	s_nop 0
	buffer_load_dwordx4 v166, s[28:31], s56 offen lds
	s_add_i32 s55, s55, 0x84000
	s_mov_b32 m0, s17
	s_nop 0
	buffer_load_dwordx4 v167, s[28:31], s56 offen lds
	s_nop 0
	s_mov_b32 m0, s34
	s_nop 0
	buffer_load_dwordx4 v166, s[28:31], s55 offen lds
	s_nop 0
	s_mov_b32 m0, s40
	s_nop 0
	buffer_load_dwordx4 v167, s[28:31], s55 offen lds
	s_nop 0
	s_mov_b32 m0, s18
	s_nop 0
	buffer_load_dwordx4 v166, s[24:27], s53 offen lds
	s_nop 0
	s_mov_b32 m0, s19
	s_nop 0
	buffer_load_dwordx4 v167, s[24:27], s53 offen lds
	ds_read_b128 v[190:193], v169 offset:49152
	ds_read_b128 v[194:197], v169 offset:50176
	ds_read_b128 v[198:201], v169 offset:51200
	ds_read_b128 v[202:205], v169 offset:52224
	ds_read_b128 v[220:223], v169 offset:53248
	ds_read_b128 v[224:227], v169 offset:54272
	ds_read_b128 v[228:231], v169 offset:55296
	ds_read_b128 v[240:243], v169 offset:56320
	s_waitcnt vmcnt(8)
	s_waitcnt lgkmcnt(0)
	s_barrier
	s_waitcnt lgkmcnt(7)
	v_mfma_f32_16x16x32_bf16 v[60:63], v[152:155], v[190:193], v[60:63]
	v_mfma_f32_16x16x32_bf16 v[52:55], v[160:163], v[190:193], v[52:55]
	s_waitcnt lgkmcnt(5)
	v_mfma_f32_16x16x32_bf16 v[44:47], v[152:155], v[198:201], v[44:47]
	v_mfma_f32_16x16x32_bf16 v[36:39], v[160:163], v[198:201], v[36:39]
	s_waitcnt lgkmcnt(3)
	v_mfma_f32_16x16x32_bf16 v[28:31], v[152:155], v[220:223], v[28:31]
	v_mfma_f32_16x16x32_bf16 v[20:23], v[160:163], v[220:223], v[20:23]
	s_waitcnt lgkmcnt(1)
	v_mfma_f32_16x16x32_bf16 v[12:15], v[152:155], v[228:231], v[12:15]
	v_mfma_f32_16x16x32_bf16 v[4:7], v[160:163], v[228:231], v[4:7]
	v_mfma_f32_16x16x32_bf16 v[60:63], v[156:159], v[194:197], v[60:63]
	v_mfma_f32_16x16x32_bf16 v[52:55], v[170:173], v[194:197], v[52:55]
	v_mfma_f32_16x16x32_bf16 v[44:47], v[156:159], v[202:205], v[44:47]
	v_mfma_f32_16x16x32_bf16 v[36:39], v[170:173], v[202:205], v[36:39]
	v_mfma_f32_16x16x32_bf16 v[28:31], v[156:159], v[224:227], v[28:31]
	v_mfma_f32_16x16x32_bf16 v[20:23], v[170:173], v[224:227], v[20:23]
	s_waitcnt lgkmcnt(0)
	v_mfma_f32_16x16x32_bf16 v[12:15], v[156:159], v[240:243], v[12:15]
	v_mfma_f32_16x16x32_bf16 v[4:7], v[170:173], v[240:243], v[4:7]
	v_mfma_f32_16x16x32_bf16 v[56:59], v[174:177], v[190:193], v[56:59]
	v_mfma_f32_16x16x32_bf16 v[48:51], v[182:185], v[190:193], v[48:51]
	v_mfma_f32_16x16x32_bf16 v[40:43], v[174:177], v[198:201], v[40:43]
	v_mfma_f32_16x16x32_bf16 v[32:35], v[182:185], v[198:201], v[32:35]
	v_mfma_f32_16x16x32_bf16 v[24:27], v[174:177], v[220:223], v[24:27]
	v_mfma_f32_16x16x32_bf16 v[16:19], v[182:185], v[220:223], v[16:19]
	v_mfma_f32_16x16x32_bf16 v[8:11], v[174:177], v[228:231], v[8:11]
	v_mfma_f32_16x16x32_bf16 v[0:3], v[182:185], v[228:231], v[0:3]
	v_mfma_f32_16x16x32_bf16 v[56:59], v[178:181], v[194:197], v[56:59]
	v_mfma_f32_16x16x32_bf16 v[48:51], v[186:189], v[194:197], v[48:51]
	v_mfma_f32_16x16x32_bf16 v[40:43], v[178:181], v[202:205], v[40:43]
	v_mfma_f32_16x16x32_bf16 v[32:35], v[186:189], v[202:205], v[32:35]
	v_mfma_f32_16x16x32_bf16 v[24:27], v[178:181], v[224:227], v[24:27]
	v_mfma_f32_16x16x32_bf16 v[16:19], v[186:189], v[224:227], v[16:19]
	v_mfma_f32_16x16x32_bf16 v[8:11], v[178:181], v[240:243], v[8:11]
	v_mfma_f32_16x16x32_bf16 v[0:3], v[186:189], v[240:243], v[0:3]
	s_barrier
	s_add_i32 s52, s52, 2
	s_add_i32 s37, s37, 0x8000
	s_add_i32 s51, s51, 0x8000
	s_cmp_gt_u32 s52, 29
	s_cbranch_scc0 .LBB0_795

.Lnb_p6:
	s_add_i32 s11, s8, 0xffea4000
	s_cmpk_eq_i32 s10, 0x54
	s_cselect_b32 s13, s6, s11
	s_cselect_b32 s12, s7, s9
	s_or_b32 s11, s13, 0x4000
	s_mov_b32 m0, s87
	s_nop 0
	buffer_load_dwordx4 v220, s[20:23], s8 offen lds
	s_nop 0
	s_mov_b32 m0, s89
	s_nop 0
	buffer_load_dwordx4 v221, s[20:23], s8 offen lds
	s_waitcnt vmcnt(24)
	s_waitcnt lgkmcnt(0)
	s_barrier
	s_waitcnt lgkmcnt(7)
	v_mfma_f32_16x16x32_bf16 v[164:167], v[128:131], v[184:187], 0
	v_mfma_f32_16x16x32_bf16 v[160:163], v[152:155], v[184:187], 0
	s_waitcnt lgkmcnt(5)
	v_mfma_f32_16x16x32_bf16 v[136:139], v[128:131], v[192:195], 0
	v_mfma_f32_16x16x32_bf16 v[132:135], v[152:155], v[192:195], 0
	s_waitcnt lgkmcnt(3)
	v_mfma_f32_16x16x32_bf16 v[116:119], v[128:131], v[200:203], 0
	v_mfma_f32_16x16x32_bf16 v[112:115], v[152:155], v[200:203], 0
	s_waitcnt lgkmcnt(1)
	v_mfma_f32_16x16x32_bf16 v[76:79], v[128:131], v[224:227], 0
	v_mfma_f32_16x16x32_bf16 v[72:75], v[152:155], v[224:227], 0
	v_mfma_f32_16x16x32_bf16 v[164:167], v[140:143], v[188:191], v[164:167]
	v_mfma_f32_16x16x32_bf16 v[160:163], v[156:159], v[188:191], v[160:163]
	v_mfma_f32_16x16x32_bf16 v[136:139], v[140:143], v[196:199], v[136:139]
	v_mfma_f32_16x16x32_bf16 v[132:135], v[156:159], v[196:199], v[132:135]
	v_mfma_f32_16x16x32_bf16 v[116:119], v[140:143], v[204:207], v[116:119]
	v_mfma_f32_16x16x32_bf16 v[112:115], v[156:159], v[204:207], v[112:115]
	s_waitcnt lgkmcnt(0)
	v_mfma_f32_16x16x32_bf16 v[76:79], v[140:143], v[228:231], v[76:79]
	v_mfma_f32_16x16x32_bf16 v[72:75], v[156:159], v[228:231], v[72:75]
	v_mfma_f32_16x16x32_bf16 v[148:151], v[168:171], v[184:187], 0
	v_mfma_f32_16x16x32_bf16 v[144:147], v[176:179], v[184:187], 0
	v_mfma_f32_16x16x32_bf16 v[124:127], v[168:171], v[192:195], 0
	v_mfma_f32_16x16x32_bf16 v[120:123], v[176:179], v[192:195], 0
	v_mfma_f32_16x16x32_bf16 v[108:111], v[168:171], v[200:203], 0
	v_mfma_f32_16x16x32_bf16 v[104:107], v[176:179], v[200:203], 0
	v_mfma_f32_16x16x32_bf16 v[68:71], v[168:171], v[224:227], 0
	v_mfma_f32_16x16x32_bf16 v[64:67], v[176:179], v[224:227], 0
	v_mfma_f32_16x16x32_bf16 v[148:151], v[172:175], v[188:191], v[148:151]
	v_mfma_f32_16x16x32_bf16 v[144:147], v[180:183], v[188:191], v[144:147]
	v_mfma_f32_16x16x32_bf16 v[124:127], v[172:175], v[196:199], v[124:127]
	v_mfma_f32_16x16x32_bf16 v[120:123], v[180:183], v[196:199], v[120:123]
	v_mfma_f32_16x16x32_bf16 v[108:111], v[172:175], v[204:207], v[108:111]
	v_mfma_f32_16x16x32_bf16 v[104:107], v[180:183], v[204:207], v[104:107]
	v_mfma_f32_16x16x32_bf16 v[68:71], v[172:175], v[228:231], v[68:71]
	v_mfma_f32_16x16x32_bf16 v[64:67], v[180:183], v[228:231], v[64:67]
	s_barrier
	s_mov_b32 m0, s51
	s_nop 0
	buffer_load_dwordx4 v220, s[52:55], s12 offen lds
	s_add_i32 s14, s12, 0x160000
	s_mov_b32 m0, s74
	s_nop 0
	buffer_load_dwordx4 v221, s[52:55], s12 offen lds
	s_nop 0
	s_mov_b32 m0, s75
	s_nop 0
	buffer_load_dwordx4 v220, s[52:55], s14 offen lds
	s_nop 0
	s_mov_b32 m0, s76
	s_nop 0
	buffer_load_dwordx4 v221, s[52:55], s14 offen lds
	s_nop 0
	s_mov_b32 m0, s31
	s_nop 0
	buffer_load_dwordx4 v220, s[20:23], s13 offen lds
	s_nop 0
	s_mov_b32 m0, s77
	s_nop 0
	buffer_load_dwordx4 v221, s[20:23], s13 offen lds
	ds_read_b128 v[184:187], v223 offset:16384
	ds_read_b128 v[188:191], v223 offset:17408
	ds_read_b128 v[192:195], v223 offset:18432
	ds_read_b128 v[196:199], v223 offset:19456
	ds_read_b128 v[200:203], v223 offset:20480
	ds_read_b128 v[204:207], v223 offset:21504
	ds_read_b128 v[224:227], v223 offset:22528
	ds_read_b128 v[228:231], v223 offset:23552
	s_waitcnt vmcnt(24)
	s_waitcnt lgkmcnt(0)
	s_barrier
	s_waitcnt lgkmcnt(7)
	v_mfma_f32_16x16x32_bf16 v[60:63], v[128:131], v[184:187], 0
	v_mfma_f32_16x16x32_bf16 v[56:59], v[152:155], v[184:187], 0
	s_waitcnt lgkmcnt(5)
	v_mfma_f32_16x16x32_bf16 v[44:47], v[128:131], v[192:195], 0
	v_mfma_f32_16x16x32_bf16 v[40:43], v[152:155], v[192:195], 0
	s_waitcnt lgkmcnt(3)
	v_mfma_f32_16x16x32_bf16 v[28:31], v[128:131], v[200:203], 0
	v_mfma_f32_16x16x32_bf16 v[24:27], v[152:155], v[200:203], 0
	s_waitcnt lgkmcnt(1)
	v_mfma_f32_16x16x32_bf16 v[12:15], v[128:131], v[224:227], 0
	v_mfma_f32_16x16x32_bf16 v[8:11], v[152:155], v[224:227], 0
	v_mfma_f32_16x16x32_bf16 v[60:63], v[140:143], v[188:191], v[60:63]
	v_mfma_f32_16x16x32_bf16 v[56:59], v[156:159], v[188:191], v[56:59]
	v_mfma_f32_16x16x32_bf16 v[44:47], v[140:143], v[196:199], v[44:47]
	v_mfma_f32_16x16x32_bf16 v[40:43], v[156:159], v[196:199], v[40:43]
	v_mfma_f32_16x16x32_bf16 v[28:31], v[140:143], v[204:207], v[28:31]
	v_mfma_f32_16x16x32_bf16 v[24:27], v[156:159], v[204:207], v[24:27]
	s_waitcnt lgkmcnt(0)
	v_mfma_f32_16x16x32_bf16 v[12:15], v[140:143], v[228:231], v[12:15]
	v_mfma_f32_16x16x32_bf16 v[8:11], v[156:159], v[228:231], v[8:11]
	v_mfma_f32_16x16x32_bf16 v[52:55], v[168:171], v[184:187], 0
	v_mfma_f32_16x16x32_bf16 v[48:51], v[176:179], v[184:187], 0
	v_mfma_f32_16x16x32_bf16 v[36:39], v[168:171], v[192:195], 0
	v_mfma_f32_16x16x32_bf16 v[32:35], v[176:179], v[192:195], 0
	v_mfma_f32_16x16x32_bf16 v[20:23], v[168:171], v[200:203], 0
	v_mfma_f32_16x16x32_bf16 v[16:19], v[176:179], v[200:203], 0
	v_mfma_f32_16x16x32_bf16 v[4:7], v[168:171], v[224:227], 0
	v_mfma_f32_16x16x32_bf16 v[0:3], v[176:179], v[224:227], 0
	v_mfma_f32_16x16x32_bf16 v[52:55], v[172:175], v[188:191], v[52:55]
	v_mfma_f32_16x16x32_bf16 v[48:51], v[180:183], v[188:191], v[48:51]
	v_mfma_f32_16x16x32_bf16 v[36:39], v[172:175], v[196:199], v[36:39]
	v_mfma_f32_16x16x32_bf16 v[32:35], v[180:183], v[196:199], v[32:35]
	v_mfma_f32_16x16x32_bf16 v[20:23], v[172:175], v[204:207], v[20:23]
	v_mfma_f32_16x16x32_bf16 v[16:19], v[180:183], v[204:207], v[16:19]
	v_mfma_f32_16x16x32_bf16 v[4:7], v[172:175], v[228:231], v[4:7]
	v_mfma_f32_16x16x32_bf16 v[0:3], v[180:183], v[228:231], v[0:3]
	s_barrier
	s_add_i32 s13, s13, 0x160000
	s_mov_b32 m0, s78
	s_nop 0
	buffer_load_dwordx4 v220, s[20:23], s13 offen lds
	s_nop 0
	s_mov_b32 m0, s79
	s_nop 0
	buffer_load_dwordx4 v221, s[20:23], s13 offen lds
	v_add_u32_e32 v156, 0x18000, v222
	v_add_u32_e32 v180, 0x1c000, v222
	ds_read_b128 v[128:131], v156
	ds_read_b128 v[140:143], v156 offset:1024
	ds_read_b128 v[152:155], v156 offset:2048
	ds_read_b128 v[156:159], v156 offset:3072
	ds_read_b128 v[168:171], v180
	ds_read_b128 v[172:175], v180 offset:1024
	ds_read_b128 v[176:179], v180 offset:2048
	ds_read_b128 v[180:183], v180 offset:3072
	ds_read_b128 v[184:187], v223 offset:32768
	ds_read_b128 v[188:191], v223 offset:33792
	ds_read_b128 v[192:195], v223 offset:34816
	ds_read_b128 v[196:199], v223 offset:35840
	ds_read_b128 v[200:203], v223 offset:36864
	ds_read_b128 v[204:207], v223 offset:37888
	ds_read_b128 v[224:227], v223 offset:38912
	ds_read_b128 v[228:231], v223 offset:39936
	s_waitcnt vmcnt(8)
	s_waitcnt lgkmcnt(0)
	s_barrier
	s_waitcnt lgkmcnt(7)
	v_mfma_f32_16x16x32_bf16 v[164:167], v[128:131], v[184:187], v[164:167]
	v_mfma_f32_16x16x32_bf16 v[160:163], v[152:155], v[184:187], v[160:163]
	s_waitcnt lgkmcnt(5)
	v_mfma_f32_16x16x32_bf16 v[136:139], v[128:131], v[192:195], v[136:139]
	v_mfma_f32_16x16x32_bf16 v[132:135], v[152:155], v[192:195], v[132:135]
	s_waitcnt lgkmcnt(3)
	v_mfma_f32_16x16x32_bf16 v[116:119], v[128:131], v[200:203], v[116:119]
	v_mfma_f32_16x16x32_bf16 v[112:115], v[152:155], v[200:203], v[112:115]
	s_waitcnt lgkmcnt(1)
	v_mfma_f32_16x16x32_bf16 v[76:79], v[128:131], v[224:227], v[76:79]
	v_mfma_f32_16x16x32_bf16 v[72:75], v[152:155], v[224:227], v[72:75]
	v_mfma_f32_16x16x32_bf16 v[164:167], v[140:143], v[188:191], v[164:167]
	v_mfma_f32_16x16x32_bf16 v[160:163], v[156:159], v[188:191], v[160:163]
	v_mfma_f32_16x16x32_bf16 v[136:139], v[140:143], v[196:199], v[136:139]
	v_mfma_f32_16x16x32_bf16 v[132:135], v[156:159], v[196:199], v[132:135]
	v_mfma_f32_16x16x32_bf16 v[116:119], v[140:143], v[204:207], v[116:119]
	v_mfma_f32_16x16x32_bf16 v[112:115], v[156:159], v[204:207], v[112:115]
	s_waitcnt lgkmcnt(0)
	v_mfma_f32_16x16x32_bf16 v[76:79], v[140:143], v[228:231], v[76:79]
	v_mfma_f32_16x16x32_bf16 v[72:75], v[156:159], v[228:231], v[72:75]
	v_mfma_f32_16x16x32_bf16 v[148:151], v[168:171], v[184:187], v[148:151]
	v_mfma_f32_16x16x32_bf16 v[144:147], v[176:179], v[184:187], v[144:147]
	v_mfma_f32_16x16x32_bf16 v[124:127], v[168:171], v[192:195], v[124:127]
	v_mfma_f32_16x16x32_bf16 v[120:123], v[176:179], v[192:195], v[120:123]
	v_mfma_f32_16x16x32_bf16 v[108:111], v[168:171], v[200:203], v[108:111]
	v_mfma_f32_16x16x32_bf16 v[104:107], v[176:179], v[200:203], v[104:107]
	v_mfma_f32_16x16x32_bf16 v[68:71], v[168:171], v[224:227], v[68:71]
	v_mfma_f32_16x16x32_bf16 v[64:67], v[176:179], v[224:227], v[64:67]
	v_mfma_f32_16x16x32_bf16 v[148:151], v[172:175], v[188:191], v[148:151]
	v_mfma_f32_16x16x32_bf16 v[144:147], v[180:183], v[188:191], v[144:147]
	v_mfma_f32_16x16x32_bf16 v[124:127], v[172:175], v[196:199], v[124:127]
	v_mfma_f32_16x16x32_bf16 v[120:123], v[180:183], v[196:199], v[120:123]
	v_mfma_f32_16x16x32_bf16 v[108:111], v[172:175], v[204:207], v[108:111]
	v_mfma_f32_16x16x32_bf16 v[104:107], v[180:183], v[204:207], v[104:107]
	v_mfma_f32_16x16x32_bf16 v[68:71], v[172:175], v[228:231], v[68:71]
	v_mfma_f32_16x16x32_bf16 v[64:67], v[180:183], v[228:231], v[64:67]
	s_barrier
	s_or_b32 s13, s12, 0x4000
	s_mov_b32 m0, s34
	s_nop 0
	buffer_load_dwordx4 v220, s[52:55], s13 offen lds
	s_add_i32 s12, s12, 0x164000
	s_mov_b32 m0, s82
	s_nop 0
	buffer_load_dwordx4 v221, s[52:55], s13 offen lds
	s_nop 0
	s_mov_b32 m0, s85
	s_nop 0
	buffer_load_dwordx4 v220, s[52:55], s12 offen lds
	s_nop 0
	s_mov_b32 m0, s86
	s_nop 0
	buffer_load_dwordx4 v221, s[52:55], s12 offen lds
	s_nop 0
	s_mov_b32 m0, s83
	s_nop 0
	buffer_load_dwordx4 v220, s[20:23], s11 offen lds
	s_nop 0
	s_mov_b32 m0, s84
	s_nop 0
	buffer_load_dwordx4 v221, s[20:23], s11 offen lds
	ds_read_b128 v[184:187], v223 offset:49152
	ds_read_b128 v[188:191], v223 offset:50176
	ds_read_b128 v[192:195], v223 offset:51200
	ds_read_b128 v[196:199], v223 offset:52224
	ds_read_b128 v[200:203], v223 offset:53248
	ds_read_b128 v[204:207], v223 offset:54272
	ds_read_b128 v[224:227], v223 offset:55296
	ds_read_b128 v[228:231], v223 offset:56320
	s_waitcnt vmcnt(8)
	s_waitcnt lgkmcnt(0)
	s_barrier
	s_waitcnt lgkmcnt(7)
	v_mfma_f32_16x16x32_bf16 v[60:63], v[128:131], v[184:187], v[60:63]
	v_mfma_f32_16x16x32_bf16 v[56:59], v[152:155], v[184:187], v[56:59]
	s_waitcnt lgkmcnt(5)
	v_mfma_f32_16x16x32_bf16 v[44:47], v[128:131], v[192:195], v[44:47]
	v_mfma_f32_16x16x32_bf16 v[40:43], v[152:155], v[192:195], v[40:43]
	s_waitcnt lgkmcnt(3)
	v_mfma_f32_16x16x32_bf16 v[28:31], v[128:131], v[200:203], v[28:31]
	v_mfma_f32_16x16x32_bf16 v[24:27], v[152:155], v[200:203], v[24:27]
	s_waitcnt lgkmcnt(1)
	v_mfma_f32_16x16x32_bf16 v[12:15], v[128:131], v[224:227], v[12:15]
	v_mfma_f32_16x16x32_bf16 v[8:11], v[152:155], v[224:227], v[8:11]
	v_mfma_f32_16x16x32_bf16 v[60:63], v[140:143], v[188:191], v[60:63]
	v_mfma_f32_16x16x32_bf16 v[56:59], v[156:159], v[188:191], v[56:59]
	v_mfma_f32_16x16x32_bf16 v[44:47], v[140:143], v[196:199], v[44:47]
	v_mfma_f32_16x16x32_bf16 v[40:43], v[156:159], v[196:199], v[40:43]
	v_mfma_f32_16x16x32_bf16 v[28:31], v[140:143], v[204:207], v[28:31]
	v_mfma_f32_16x16x32_bf16 v[24:27], v[156:159], v[204:207], v[24:27]
	s_waitcnt lgkmcnt(0)
	v_mfma_f32_16x16x32_bf16 v[12:15], v[140:143], v[228:231], v[12:15]
	v_mfma_f32_16x16x32_bf16 v[8:11], v[156:159], v[228:231], v[8:11]
	v_mfma_f32_16x16x32_bf16 v[52:55], v[168:171], v[184:187], v[52:55]
	v_mfma_f32_16x16x32_bf16 v[48:51], v[176:179], v[184:187], v[48:51]
	v_mfma_f32_16x16x32_bf16 v[36:39], v[168:171], v[192:195], v[36:39]
	v_mfma_f32_16x16x32_bf16 v[32:35], v[176:179], v[192:195], v[32:35]
	v_mfma_f32_16x16x32_bf16 v[20:23], v[168:171], v[200:203], v[20:23]
	v_mfma_f32_16x16x32_bf16 v[16:19], v[176:179], v[200:203], v[16:19]
	v_mfma_f32_16x16x32_bf16 v[4:7], v[168:171], v[224:227], v[4:7]
	v_mfma_f32_16x16x32_bf16 v[0:3], v[176:179], v[224:227], v[0:3]
	v_mfma_f32_16x16x32_bf16 v[52:55], v[172:175], v[188:191], v[52:55]
	v_mfma_f32_16x16x32_bf16 v[48:51], v[180:183], v[188:191], v[48:51]
	v_mfma_f32_16x16x32_bf16 v[36:39], v[172:175], v[196:199], v[36:39]
	v_mfma_f32_16x16x32_bf16 v[32:35], v[180:183], v[196:199], v[32:35]
	v_mfma_f32_16x16x32_bf16 v[20:23], v[172:175], v[204:207], v[20:23]
	v_mfma_f32_16x16x32_bf16 v[16:19], v[180:183], v[204:207], v[16:19]
	v_mfma_f32_16x16x32_bf16 v[4:7], v[172:175], v[228:231], v[4:7]
	v_mfma_f32_16x16x32_bf16 v[0:3], v[180:183], v[228:231], v[0:3]
	s_barrier
	s_add_i32 s10, s10, 2
	s_add_i32 s8, s8, 0x8000
	s_add_i32 s9, s9, 0x8000
.LBB0_885:
	v_add_u32_e32 v156, 0x10000, v222
	v_add_u32_e32 v180, 0x14000, v222
	ds_read_b128 v[128:131], v156
	ds_read_b128 v[140:143], v156 offset:1024
	ds_read_b128 v[152:155], v156 offset:2048
	ds_read_b128 v[156:159], v156 offset:3072
	ds_read_b128 v[168:171], v180
	ds_read_b128 v[172:175], v180 offset:1024
	ds_read_b128 v[176:179], v180 offset:2048
	ds_read_b128 v[180:183], v180 offset:3072
	s_add_i32 s11, s8, 0xffea4000
	s_cmpk_eq_i32 s10, 0x54
	s_cselect_b32 s13, s6, s11
	s_cselect_b32 s12, s7, s9
	s_or_b32 s11, s13, 0x4000
	ds_read_b128 v[184:187], v223
	ds_read_b128 v[188:191], v223 offset:1024
	ds_read_b128 v[192:195], v223 offset:2048
	ds_read_b128 v[196:199], v223 offset:3072
	ds_read_b128 v[200:203], v223 offset:4096
	ds_read_b128 v[204:207], v223 offset:5120
	ds_read_b128 v[224:227], v223 offset:6144
	ds_read_b128 v[228:231], v223 offset:7168
	s_mov_b32 m0, s87
	s_nop 0
	buffer_load_dwordx4 v220, s[20:23], s8 offen lds
	s_nop 0
	s_mov_b32 m0, s89
	s_nop 0
	buffer_load_dwordx4 v221, s[20:23], s8 offen lds
	s_waitcnt vmcnt(8)
	s_waitcnt lgkmcnt(0)
	s_barrier
	s_waitcnt lgkmcnt(7)
	v_mfma_f32_16x16x32_bf16 v[164:167], v[128:131], v[184:187], v[164:167]
	v_mfma_f32_16x16x32_bf16 v[160:163], v[152:155], v[184:187], v[160:163]
	s_waitcnt lgkmcnt(5)
	v_mfma_f32_16x16x32_bf16 v[136:139], v[128:131], v[192:195], v[136:139]
	v_mfma_f32_16x16x32_bf16 v[132:135], v[152:155], v[192:195], v[132:135]
	s_waitcnt lgkmcnt(3)
	v_mfma_f32_16x16x32_bf16 v[116:119], v[128:131], v[200:203], v[116:119]
	v_mfma_f32_16x16x32_bf16 v[112:115], v[152:155], v[200:203], v[112:115]
	s_waitcnt lgkmcnt(1)
	v_mfma_f32_16x16x32_bf16 v[76:79], v[128:131], v[224:227], v[76:79]
	v_mfma_f32_16x16x32_bf16 v[72:75], v[152:155], v[224:227], v[72:75]
	v_mfma_f32_16x16x32_bf16 v[164:167], v[140:143], v[188:191], v[164:167]
	v_mfma_f32_16x16x32_bf16 v[160:163], v[156:159], v[188:191], v[160:163]
	v_mfma_f32_16x16x32_bf16 v[136:139], v[140:143], v[196:199], v[136:139]
	v_mfma_f32_16x16x32_bf16 v[132:135], v[156:159], v[196:199], v[132:135]
	v_mfma_f32_16x16x32_bf16 v[116:119], v[140:143], v[204:207], v[116:119]
	v_mfma_f32_16x16x32_bf16 v[112:115], v[156:159], v[204:207], v[112:115]
	s_waitcnt lgkmcnt(0)
	v_mfma_f32_16x16x32_bf16 v[76:79], v[140:143], v[228:231], v[76:79]
	v_mfma_f32_16x16x32_bf16 v[72:75], v[156:159], v[228:231], v[72:75]
	v_mfma_f32_16x16x32_bf16 v[148:151], v[168:171], v[184:187], v[148:151]
	v_mfma_f32_16x16x32_bf16 v[144:147], v[176:179], v[184:187], v[144:147]
	v_mfma_f32_16x16x32_bf16 v[124:127], v[168:171], v[192:195], v[124:127]
	v_mfma_f32_16x16x32_bf16 v[120:123], v[176:179], v[192:195], v[120:123]
	v_mfma_f32_16x16x32_bf16 v[108:111], v[168:171], v[200:203], v[108:111]
	v_mfma_f32_16x16x32_bf16 v[104:107], v[176:179], v[200:203], v[104:107]
	v_mfma_f32_16x16x32_bf16 v[68:71], v[168:171], v[224:227], v[68:71]
	v_mfma_f32_16x16x32_bf16 v[64:67], v[176:179], v[224:227], v[64:67]
	v_mfma_f32_16x16x32_bf16 v[148:151], v[172:175], v[188:191], v[148:151]
	v_mfma_f32_16x16x32_bf16 v[144:147], v[180:183], v[188:191], v[144:147]
	v_mfma_f32_16x16x32_bf16 v[124:127], v[172:175], v[196:199], v[124:127]
	v_mfma_f32_16x16x32_bf16 v[120:123], v[180:183], v[196:199], v[120:123]
	v_mfma_f32_16x16x32_bf16 v[108:111], v[172:175], v[204:207], v[108:111]
	v_mfma_f32_16x16x32_bf16 v[104:107], v[180:183], v[204:207], v[104:107]
	v_mfma_f32_16x16x32_bf16 v[68:71], v[172:175], v[228:231], v[68:71]
	v_mfma_f32_16x16x32_bf16 v[64:67], v[180:183], v[228:231], v[64:67]
	s_barrier
	s_mov_b32 m0, s51
	s_nop 0
	buffer_load_dwordx4 v220, s[52:55], s12 offen lds
	s_add_i32 s14, s12, 0x160000
	s_mov_b32 m0, s74
	s_nop 0
	buffer_load_dwordx4 v221, s[52:55], s12 offen lds
	s_nop 0
	s_mov_b32 m0, s75
	s_nop 0
	buffer_load_dwordx4 v220, s[52:55], s14 offen lds
	s_nop 0
	s_mov_b32 m0, s76
	s_nop 0
	buffer_load_dwordx4 v221, s[52:55], s14 offen lds
	s_nop 0
	s_mov_b32 m0, s31
	s_nop 0
	buffer_load_dwordx4 v220, s[20:23], s13 offen lds
	s_nop 0
	s_mov_b32 m0, s77
	s_nop 0
	buffer_load_dwordx4 v221, s[20:23], s13 offen lds
	ds_read_b128 v[184:187], v223 offset:16384
	ds_read_b128 v[188:191], v223 offset:17408
	ds_read_b128 v[192:195], v223 offset:18432
	ds_read_b128 v[196:199], v223 offset:19456
	ds_read_b128 v[200:203], v223 offset:20480
	ds_read_b128 v[204:207], v223 offset:21504
	ds_read_b128 v[224:227], v223 offset:22528
	ds_read_b128 v[228:231], v223 offset:23552
	s_waitcnt vmcnt(8)
	s_waitcnt lgkmcnt(0)
	s_barrier
	s_waitcnt lgkmcnt(7)
	v_mfma_f32_16x16x32_bf16 v[60:63], v[128:131], v[184:187], v[60:63]
	v_mfma_f32_16x16x32_bf16 v[56:59], v[152:155], v[184:187], v[56:59]
	s_waitcnt lgkmcnt(5)
	v_mfma_f32_16x16x32_bf16 v[44:47], v[128:131], v[192:195], v[44:47]
	v_mfma_f32_16x16x32_bf16 v[40:43], v[152:155], v[192:195], v[40:43]
	s_waitcnt lgkmcnt(3)
	v_mfma_f32_16x16x32_bf16 v[28:31], v[128:131], v[200:203], v[28:31]
	v_mfma_f32_16x16x32_bf16 v[24:27], v[152:155], v[200:203], v[24:27]
	s_waitcnt lgkmcnt(1)
	v_mfma_f32_16x16x32_bf16 v[12:15], v[128:131], v[224:227], v[12:15]
	v_mfma_f32_16x16x32_bf16 v[8:11], v[152:155], v[224:227], v[8:11]
	v_mfma_f32_16x16x32_bf16 v[60:63], v[140:143], v[188:191], v[60:63]
	v_mfma_f32_16x16x32_bf16 v[56:59], v[156:159], v[188:191], v[56:59]
	v_mfma_f32_16x16x32_bf16 v[44:47], v[140:143], v[196:199], v[44:47]
	v_mfma_f32_16x16x32_bf16 v[40:43], v[156:159], v[196:199], v[40:43]
	v_mfma_f32_16x16x32_bf16 v[28:31], v[140:143], v[204:207], v[28:31]
	v_mfma_f32_16x16x32_bf16 v[24:27], v[156:159], v[204:207], v[24:27]
	s_waitcnt lgkmcnt(0)
	v_mfma_f32_16x16x32_bf16 v[12:15], v[140:143], v[228:231], v[12:15]
	v_mfma_f32_16x16x32_bf16 v[8:11], v[156:159], v[228:231], v[8:11]
	v_mfma_f32_16x16x32_bf16 v[52:55], v[168:171], v[184:187], v[52:55]
	v_mfma_f32_16x16x32_bf16 v[48:51], v[176:179], v[184:187], v[48:51]
	v_mfma_f32_16x16x32_bf16 v[36:39], v[168:171], v[192:195], v[36:39]
	v_mfma_f32_16x16x32_bf16 v[32:35], v[176:179], v[192:195], v[32:35]
	v_mfma_f32_16x16x32_bf16 v[20:23], v[168:171], v[200:203], v[20:23]
	v_mfma_f32_16x16x32_bf16 v[16:19], v[176:179], v[200:203], v[16:19]
	v_mfma_f32_16x16x32_bf16 v[4:7], v[168:171], v[224:227], v[4:7]
	v_mfma_f32_16x16x32_bf16 v[0:3], v[176:179], v[224:227], v[0:3]
	v_mfma_f32_16x16x32_bf16 v[52:55], v[172:175], v[188:191], v[52:55]
	v_mfma_f32_16x16x32_bf16 v[48:51], v[180:183], v[188:191], v[48:51]
	v_mfma_f32_16x16x32_bf16 v[36:39], v[172:175], v[196:199], v[36:39]
	v_mfma_f32_16x16x32_bf16 v[32:35], v[180:183], v[196:199], v[32:35]
	v_mfma_f32_16x16x32_bf16 v[20:23], v[172:175], v[204:207], v[20:23]
	v_mfma_f32_16x16x32_bf16 v[16:19], v[180:183], v[204:207], v[16:19]
	v_mfma_f32_16x16x32_bf16 v[4:7], v[172:175], v[228:231], v[4:7]
	v_mfma_f32_16x16x32_bf16 v[0:3], v[180:183], v[228:231], v[0:3]
	s_barrier
	s_add_i32 s13, s13, 0x160000
	s_mov_b32 m0, s78
	s_nop 0
	buffer_load_dwordx4 v220, s[20:23], s13 offen lds
	s_nop 0
	s_mov_b32 m0, s79
	s_nop 0
	buffer_load_dwordx4 v221, s[20:23], s13 offen lds
	v_add_u32_e32 v156, 0x18000, v222
	v_add_u32_e32 v180, 0x1c000, v222
	ds_read_b128 v[128:131], v156
	ds_read_b128 v[140:143], v156 offset:1024
	ds_read_b128 v[152:155], v156 offset:2048
	ds_read_b128 v[156:159], v156 offset:3072
	ds_read_b128 v[168:171], v180
	ds_read_b128 v[172:175], v180 offset:1024
	ds_read_b128 v[176:179], v180 offset:2048
	ds_read_b128 v[180:183], v180 offset:3072
	ds_read_b128 v[184:187], v223 offset:32768
	ds_read_b128 v[188:191], v223 offset:33792
	ds_read_b128 v[192:195], v223 offset:34816
	ds_read_b128 v[196:199], v223 offset:35840
	ds_read_b128 v[200:203], v223 offset:36864
	ds_read_b128 v[204:207], v223 offset:37888
	ds_read_b128 v[224:227], v223 offset:38912
	ds_read_b128 v[228:231], v223 offset:39936
	s_waitcnt vmcnt(8)
	s_waitcnt lgkmcnt(0)
	s_barrier
	s_waitcnt lgkmcnt(7)
	v_mfma_f32_16x16x32_bf16 v[164:167], v[128:131], v[184:187], v[164:167]
	v_mfma_f32_16x16x32_bf16 v[160:163], v[152:155], v[184:187], v[160:163]
	s_waitcnt lgkmcnt(5)
	v_mfma_f32_16x16x32_bf16 v[136:139], v[128:131], v[192:195], v[136:139]
	v_mfma_f32_16x16x32_bf16 v[132:135], v[152:155], v[192:195], v[132:135]
	s_waitcnt lgkmcnt(3)
	v_mfma_f32_16x16x32_bf16 v[116:119], v[128:131], v[200:203], v[116:119]
	v_mfma_f32_16x16x32_bf16 v[112:115], v[152:155], v[200:203], v[112:115]
	s_waitcnt lgkmcnt(1)
	v_mfma_f32_16x16x32_bf16 v[76:79], v[128:131], v[224:227], v[76:79]
	v_mfma_f32_16x16x32_bf16 v[72:75], v[152:155], v[224:227], v[72:75]
	v_mfma_f32_16x16x32_bf16 v[164:167], v[140:143], v[188:191], v[164:167]
	v_mfma_f32_16x16x32_bf16 v[160:163], v[156:159], v[188:191], v[160:163]
	v_mfma_f32_16x16x32_bf16 v[136:139], v[140:143], v[196:199], v[136:139]
	v_mfma_f32_16x16x32_bf16 v[132:135], v[156:159], v[196:199], v[132:135]
	v_mfma_f32_16x16x32_bf16 v[116:119], v[140:143], v[204:207], v[116:119]
	v_mfma_f32_16x16x32_bf16 v[112:115], v[156:159], v[204:207], v[112:115]
	s_waitcnt lgkmcnt(0)
	v_mfma_f32_16x16x32_bf16 v[76:79], v[140:143], v[228:231], v[76:79]
	v_mfma_f32_16x16x32_bf16 v[72:75], v[156:159], v[228:231], v[72:75]
	v_mfma_f32_16x16x32_bf16 v[148:151], v[168:171], v[184:187], v[148:151]
	v_mfma_f32_16x16x32_bf16 v[144:147], v[176:179], v[184:187], v[144:147]
	v_mfma_f32_16x16x32_bf16 v[124:127], v[168:171], v[192:195], v[124:127]
	v_mfma_f32_16x16x32_bf16 v[120:123], v[176:179], v[192:195], v[120:123]
	v_mfma_f32_16x16x32_bf16 v[108:111], v[168:171], v[200:203], v[108:111]
	v_mfma_f32_16x16x32_bf16 v[104:107], v[176:179], v[200:203], v[104:107]
	v_mfma_f32_16x16x32_bf16 v[68:71], v[168:171], v[224:227], v[68:71]
	v_mfma_f32_16x16x32_bf16 v[64:67], v[176:179], v[224:227], v[64:67]
	v_mfma_f32_16x16x32_bf16 v[148:151], v[172:175], v[188:191], v[148:151]
	v_mfma_f32_16x16x32_bf16 v[144:147], v[180:183], v[188:191], v[144:147]
	v_mfma_f32_16x16x32_bf16 v[124:127], v[172:175], v[196:199], v[124:127]
	v_mfma_f32_16x16x32_bf16 v[120:123], v[180:183], v[196:199], v[120:123]
	v_mfma_f32_16x16x32_bf16 v[108:111], v[172:175], v[204:207], v[108:111]
	v_mfma_f32_16x16x32_bf16 v[104:107], v[180:183], v[204:207], v[104:107]
	v_mfma_f32_16x16x32_bf16 v[68:71], v[172:175], v[228:231], v[68:71]
	v_mfma_f32_16x16x32_bf16 v[64:67], v[180:183], v[228:231], v[64:67]
	s_barrier
	s_or_b32 s13, s12, 0x4000
	s_mov_b32 m0, s34
	s_nop 0
	buffer_load_dwordx4 v220, s[52:55], s13 offen lds
	s_add_i32 s12, s12, 0x164000
	s_mov_b32 m0, s82
	s_nop 0
	buffer_load_dwordx4 v221, s[52:55], s13 offen lds
	s_nop 0
	s_mov_b32 m0, s85
	s_nop 0
	buffer_load_dwordx4 v220, s[52:55], s12 offen lds
	s_nop 0
	s_mov_b32 m0, s86
	s_nop 0
	buffer_load_dwordx4 v221, s[52:55], s12 offen lds
	s_nop 0
	s_mov_b32 m0, s83
	s_nop 0
	buffer_load_dwordx4 v220, s[20:23], s11 offen lds
	s_nop 0
	s_mov_b32 m0, s84
	s_nop 0
	buffer_load_dwordx4 v221, s[20:23], s11 offen lds
	ds_read_b128 v[184:187], v223 offset:49152
	ds_read_b128 v[188:191], v223 offset:50176
	ds_read_b128 v[192:195], v223 offset:51200
	ds_read_b128 v[196:199], v223 offset:52224
	ds_read_b128 v[200:203], v223 offset:53248
	ds_read_b128 v[204:207], v223 offset:54272
	ds_read_b128 v[224:227], v223 offset:55296
	ds_read_b128 v[228:231], v223 offset:56320
	s_waitcnt vmcnt(8)
	s_waitcnt lgkmcnt(0)
	s_barrier
	s_waitcnt lgkmcnt(7)
	v_mfma_f32_16x16x32_bf16 v[60:63], v[128:131], v[184:187], v[60:63]
	v_mfma_f32_16x16x32_bf16 v[56:59], v[152:155], v[184:187], v[56:59]
	s_waitcnt lgkmcnt(5)
	v_mfma_f32_16x16x32_bf16 v[44:47], v[128:131], v[192:195], v[44:47]
	v_mfma_f32_16x16x32_bf16 v[40:43], v[152:155], v[192:195], v[40:43]
	s_waitcnt lgkmcnt(3)
	v_mfma_f32_16x16x32_bf16 v[28:31], v[128:131], v[200:203], v[28:31]
	v_mfma_f32_16x16x32_bf16 v[24:27], v[152:155], v[200:203], v[24:27]
	s_waitcnt lgkmcnt(1)
	v_mfma_f32_16x16x32_bf16 v[12:15], v[128:131], v[224:227], v[12:15]
	v_mfma_f32_16x16x32_bf16 v[8:11], v[152:155], v[224:227], v[8:11]
	v_mfma_f32_16x16x32_bf16 v[60:63], v[140:143], v[188:191], v[60:63]
	v_mfma_f32_16x16x32_bf16 v[56:59], v[156:159], v[188:191], v[56:59]
	v_mfma_f32_16x16x32_bf16 v[44:47], v[140:143], v[196:199], v[44:47]
	v_mfma_f32_16x16x32_bf16 v[40:43], v[156:159], v[196:199], v[40:43]
	v_mfma_f32_16x16x32_bf16 v[28:31], v[140:143], v[204:207], v[28:31]
	v_mfma_f32_16x16x32_bf16 v[24:27], v[156:159], v[204:207], v[24:27]
	s_waitcnt lgkmcnt(0)
	v_mfma_f32_16x16x32_bf16 v[12:15], v[140:143], v[228:231], v[12:15]
	v_mfma_f32_16x16x32_bf16 v[8:11], v[156:159], v[228:231], v[8:11]
	v_mfma_f32_16x16x32_bf16 v[52:55], v[168:171], v[184:187], v[52:55]
	v_mfma_f32_16x16x32_bf16 v[48:51], v[176:179], v[184:187], v[48:51]
	v_mfma_f32_16x16x32_bf16 v[36:39], v[168:171], v[192:195], v[36:39]
	v_mfma_f32_16x16x32_bf16 v[32:35], v[176:179], v[192:195], v[32:35]
	v_mfma_f32_16x16x32_bf16 v[20:23], v[168:171], v[200:203], v[20:23]
	v_mfma_f32_16x16x32_bf16 v[16:19], v[176:179], v[200:203], v[16:19]
	v_mfma_f32_16x16x32_bf16 v[4:7], v[168:171], v[224:227], v[4:7]
	v_mfma_f32_16x16x32_bf16 v[0:3], v[176:179], v[224:227], v[0:3]
	v_mfma_f32_16x16x32_bf16 v[52:55], v[172:175], v[188:191], v[52:55]
	v_mfma_f32_16x16x32_bf16 v[48:51], v[180:183], v[188:191], v[48:51]
	v_mfma_f32_16x16x32_bf16 v[36:39], v[172:175], v[196:199], v[36:39]
	v_mfma_f32_16x16x32_bf16 v[32:35], v[180:183], v[196:199], v[32:35]
	v_mfma_f32_16x16x32_bf16 v[20:23], v[172:175], v[204:207], v[20:23]
	v_mfma_f32_16x16x32_bf16 v[16:19], v[180:183], v[204:207], v[16:19]
	v_mfma_f32_16x16x32_bf16 v[4:7], v[172:175], v[228:231], v[4:7]
	v_mfma_f32_16x16x32_bf16 v[0:3], v[180:183], v[228:231], v[0:3]
	s_barrier
	s_add_i32 s10, s10, 2
	s_add_i32 s8, s8, 0x8000
	s_add_i32 s9, s9, 0x8000
	s_cmpk_gt_u32 s10, 0x55
	s_cbranch_scc0 .LBB0_885
